# combination plus log2(e) folded into the sigmoid column scales (one v_mul per element removed in SwiGLU and gate epilogues; always-true sigmoid select dropped)
# baseline (speedup 1.0000x reference)
.LBB0_211:
	v_lshl_or_b32 v170, s72, 7, v156
	v_ashrrev_i32_e32 v171, 31, v170
	v_lshlrev_b64 v[148:149], 2, v[170:171]
	v_lshl_add_u64 v[150:151], s[10:11], 0, v[148:149]
	v_lshl_add_u64 v[148:149], s[24:25], 0, v[148:149]
	global_load_dwordx4 v[152:155], v[150:151], off
	global_load_dwordx4 v[158:161], v[148:149], off
	global_load_dwordx4 v[162:165], v[150:151], off offset:16
	global_load_dwordx4 v[166:169], v[148:149], off offset:16
	v_lshl_add_u32 v148, s48, 8, v1
	v_ashrrev_i32_e32 v149, 31, v148
	v_lshl_add_u64 v[150:151], v[148:149], 2, s[26:27]
	global_load_dword v172, v[150:151], off
	global_load_dword v192, v[150:151], off offset:64
	global_load_dword v194, v[150:151], off offset:128
	global_load_dword v196, v[150:151], off offset:192
	global_load_dword v198, v[150:151], off offset:512
	global_load_dword v200, v[150:151], off offset:576
	global_load_dword v202, v[150:151], off offset:640
	global_load_dword v204, v[150:151], off offset:704
	v_cvt_f32_i32_e32 v175, v126
	v_cvt_f32_i32_e32 v174, v122
	v_cvt_f32_i32_e32 v177, v127
	v_cvt_f32_i32_e32 v176, v123
	v_cvt_f32_i32_e32 v179, v128
	v_cvt_f32_i32_e32 v178, v124
	v_cvt_f32_i32_e32 v180, v125
	v_cvt_f32_i32_e32 v187, v120
	v_cvt_f32_i32_e32 v189, v121
	v_cvt_f32_i32_e32 v181, v129
	v_cvt_f32_i32_e32 v183, v118
	v_cvt_f32_i32_e32 v182, v114
	v_cvt_f32_i32_e32 v185, v119
	v_cvt_f32_i32_e32 v184, v115
	v_cvt_f32_i32_e32 v186, v116
	v_cvt_f32_i32_e32 v188, v117
	v_cvt_f32_i32_e32 v111, v111
	v_cvt_f32_i32_e32 v103, v103
	v_cvt_f32_i32_e32 v113, v113
	v_cvt_f32_i32_e32 v105, v105
	v_cvt_f32_i32_e32 v95, v95
	v_cvt_f32_i32_e32 v87, v87
	v_cvt_f32_i32_e32 v97, v97
	v_cvt_f32_i32_e32 v89, v89
	v_cvt_f32_i32_e32 v79, v79
	v_cvt_f32_i32_e32 v71, v71
	v_cvt_f32_i32_e32 v81, v81
	v_cvt_f32_i32_e32 v73, v73
	v_cvt_f32_i32_e32 v63, v63
	v_cvt_f32_i32_e32 v55, v55
	v_cvt_f32_i32_e32 v65, v65
	v_cvt_f32_i32_e32 v57, v57
	v_cvt_f32_i32_e32 v47, v47
	v_cvt_f32_i32_e32 v49, v49
	v_cvt_f32_i32_e32 v39, v39
	v_cvt_f32_i32_e32 v41, v41
	v_cvt_f32_i32_e32 v31, v31
	v_cvt_f32_i32_e32 v33, v33
	v_cvt_f32_i32_e32 v23, v23
	v_cvt_f32_i32_e32 v25, v25
	v_cvt_f32_i32_e32 v15, v15
	v_cvt_f32_i32_e32 v17, v17
	v_cvt_f32_i32_e32 v7, v7
	v_cvt_f32_i32_e32 v9, v9
	s_andn2_b64 vcc, exec, s[6:7]
	s_waitcnt vmcnt(0)
	s_mov_b32 s98, 0x3c3a1e78
	s_mov_b32 s100, 0x3bb2d7c8
	v_pk_mul_f32 v[124:125], v[158:159], s[100:101] op_sel_hi:[1,0]
	v_pk_mul_f32 v[120:121], v[152:153], s[98:99] op_sel_hi:[1,0]
	v_pk_mul_f32 v[116:117], v[154:155], s[98:99] op_sel_hi:[1,0]
	v_pk_mul_f32 v[126:127], v[160:161], s[100:101] op_sel_hi:[1,0]
	v_pk_mul_f32 v[114:115], v[164:165], s[98:99] op_sel_hi:[1,0]
	v_pk_mul_f32 v[118:119], v[162:163], s[98:99] op_sel_hi:[1,0]
	v_pk_mul_f32 v[152:153], v[168:169], s[100:101] op_sel_hi:[1,0]
	v_pk_mul_f32 v[128:129], v[166:167], s[100:101] op_sel_hi:[1,0]
	v_mov_b32_e32 v122, v124
	v_mov_b32_e32 v123, v120
	v_mov_b32_e32 v120, v125
	v_mov_b32_e32 v124, v126
	v_mov_b32_e32 v125, v116
	v_mov_b32_e32 v116, v127
	v_mov_b32_e32 v126, v128
	v_mov_b32_e32 v127, v118
	v_mov_b32_e32 v118, v129
	v_mov_b32_e32 v128, v152
	v_mov_b32_e32 v129, v114
	v_mov_b32_e32 v114, v153
	v_pk_mul_f32 v[152:153], v[122:123], v[172:173] op_sel_hi:[1,0]
	v_pk_mul_f32 v[154:155], v[120:121], v[172:173] op_sel_hi:[1,0]
	v_pk_mul_f32 v[158:159], v[124:125], v[172:173] op_sel_hi:[1,0]
	v_pk_mul_f32 v[152:153], v[152:153], v[174:175]
	v_pk_mul_f32 v[154:155], v[154:155], v[176:177]
	v_pk_mul_f32 v[160:161], v[116:117], v[172:173] op_sel_hi:[1,0]
	v_pk_mul_f32 v[162:163], v[172:173], v[126:127] op_sel_hi:[0,1]
	v_pk_mul_f32 v[164:165], v[172:173], v[118:119] op_sel_hi:[0,1]
	v_pk_mul_f32 v[166:167], v[172:173], v[128:129] op_sel_hi:[0,1]
	v_pk_mul_f32 v[168:169], v[172:173], v[114:115] op_sel_hi:[0,1]
	v_pk_mul_f32 v[158:159], v[158:159], v[178:179]
	v_exp_f32_e64 v149, -v153
	v_exp_f32_e64 v172, -v155
	v_exp_f32_e64 v173, -v159
	v_pk_mul_f32 v[160:161], v[160:161], v[180:181]
	v_add_f32_e32 v149, 1.0, v149
	v_add_f32_e32 v172, 1.0, v172
	v_pk_mul_f32 v[162:163], v[162:163], v[182:183]
	v_add_f32_e32 v173, 1.0, v173
	v_rcp_f32_e32 v149, v149
	v_rcp_f32_e32 v172, v172
	v_rcp_f32_e32 v173, v173
	v_exp_f32_e64 v174, -v161
	v_exp_f32_e64 v175, -v163
	v_mul_f32_e32 v149, v153, v149
	v_mul_f32_e32 v153, v155, v172
	v_pk_mul_f32 v[164:165], v[164:165], v[184:185]
	v_mul_f32_e32 v155, v159, v173
	v_mul_f32_e32 v149, v152, v149
	v_mul_f32_e32 v154, v154, v153
	v_pk_mul_f32 v[152:153], v[168:169], v[188:189]
	v_pk_mul_f32 v[166:167], v[166:167], v[186:187]
	v_add_f32_e32 v174, 1.0, v174
	v_add_f32_e32 v175, 1.0, v175
	v_mul_f32_e32 v155, v158, v155
	v_exp_f32_e64 v176, -v165
	v_rcp_f32_e32 v174, v174
	v_rcp_f32_e32 v175, v175
	v_exp_f32_e64 v158, -v153
	v_exp_f32_e64 v177, -v167
	v_add_f32_e32 v176, 1.0, v176
	v_mul_f32_e32 v159, v161, v174
	v_mul_f32_e32 v161, v163, v175
	v_add_f32_e32 v158, 1.0, v158
	v_rcp_f32_e32 v176, v176
	v_mul_f32_e32 v159, v160, v159
	v_mul_f32_e32 v160, v162, v161
	v_add_f32_e32 v162, 1.0, v177
	v_rcp_f32_e32 v158, v158
	v_rcp_f32_e32 v162, v162
	v_mul_f32_e32 v161, v165, v176
	v_mul_f32_e32 v161, v164, v161
	v_mul_f32_e32 v153, v153, v158
	v_mul_f32_e32 v162, v167, v162
	v_mul_f32_e32 v152, v152, v153
	v_mul_f32_e32 v162, v166, v162
	v_cvt_pk_bf16_f32 v158, v149, v154
	v_cvt_pk_bf16_f32 v159, v155, v159
	v_cvt_pk_bf16_f32 v160, v160, v161
	v_cvt_pk_bf16_f32 v161, v162, v152
	v_mov_b64_e32 v[152:153], s[36:37]
	v_mad_i64_i32 v[162:163], s[0:1], v148, s71, v[152:153]
	v_lshlrev_b64 v[154:155], 1, v[170:171]
	v_lshl_add_u64 v[162:163], v[162:163], 0, v[154:155]
	global_store_dwordx4 v[162:163], v[158:161], off
	v_cvt_f32_i32_e32 v163, v110
	v_cvt_f32_i32_e32 v162, v106
	v_or_b32_e32 v158, 16, v148
	v_ashrrev_i32_e32 v159, 31, v158
	v_lshl_add_u64 v[160:161], v[158:159], 2, s[26:27]
	s_nop 1
	v_cvt_f32_i32_e32 v110, v107
	v_cvt_f32_i32_e32 v107, v112
	v_cvt_f32_i32_e32 v106, v108
	v_cvt_f32_i32_e32 v112, v109
	v_cvt_f32_i32_e32 v109, v102
	v_cvt_f32_i32_e32 v108, v98
	v_cvt_f32_i32_e32 v102, v99
	v_cvt_f32_i32_e32 v99, v104
	v_cvt_f32_i32_e32 v98, v100
	v_cvt_f32_i32_e32 v104, v101
	v_mov_b32_e32 v160, v192
	v_pk_mul_f32 v[170:171], v[126:127], v[160:161] op_sel_hi:[1,0]
	v_pk_mul_f32 v[100:101], v[122:123], v[160:161] op_sel_hi:[1,0]
	v_pk_mul_f32 v[108:109], v[170:171], v[108:109]
	v_pk_mul_f32 v[100:101], v[100:101], v[162:163]
	v_pk_mul_f32 v[164:165], v[120:121], v[160:161] op_sel_hi:[1,0]
	v_exp_f32_e64 v162, -v109
	v_pk_mul_f32 v[110:111], v[164:165], v[110:111]
	v_exp_f32_e64 v149, -v101
	v_exp_f32_e64 v159, -v111
	v_add_f32_e32 v162, 1.0, v162
	v_rcp_f32_e32 v162, v162
	v_pk_mul_f32 v[172:173], v[118:119], v[160:161] op_sel_hi:[1,0]
	v_pk_mul_f32 v[174:175], v[128:129], v[160:161] op_sel_hi:[1,0]
	v_pk_mul_f32 v[166:167], v[124:125], v[160:161] op_sel_hi:[1,0]
	v_pk_mul_f32 v[168:169], v[116:117], v[160:161] op_sel_hi:[1,0]
	v_pk_mul_f32 v[160:161], v[114:115], v[160:161] op_sel_hi:[1,0]
	v_pk_mul_f32 v[102:103], v[172:173], v[102:103]
	v_pk_mul_f32 v[98:99], v[174:175], v[98:99]
	v_add_f32_e32 v149, 1.0, v149
	v_add_f32_e32 v159, 1.0, v159
	v_pk_mul_f32 v[106:107], v[166:167], v[106:107]
	v_pk_mul_f32 v[112:113], v[168:169], v[112:113]
	v_pk_mul_f32 v[104:105], v[160:161], v[104:105]
	v_rcp_f32_e32 v149, v149
	v_rcp_f32_e32 v159, v159
	v_exp_f32_e64 v163, -v103
	v_exp_f32_e64 v164, -v99
	v_mul_f32_e32 v109, v109, v162
	v_exp_f32_e64 v160, -v107
	v_exp_f32_e64 v161, -v113
	v_mul_f32_e32 v108, v108, v109
	v_exp_f32_e64 v109, -v105
	v_mul_f32_e32 v101, v101, v149
	v_mul_f32_e32 v111, v111, v159
	v_add_f32_e32 v163, 1.0, v163
	v_mul_f32_e32 v100, v100, v101
	v_mul_f32_e32 v101, v110, v111
	v_add_f32_e32 v110, 1.0, v164
	v_add_f32_e32 v160, 1.0, v160
	v_add_f32_e32 v161, 1.0, v161
	v_rcp_f32_e32 v163, v163
	v_rcp_f32_e32 v110, v110
	v_add_f32_e32 v109, 1.0, v109
	v_rcp_f32_e32 v160, v160
	v_rcp_f32_e32 v161, v161
	v_rcp_f32_e32 v109, v109
	v_mul_f32_e32 v103, v103, v163
	v_mul_f32_e32 v99, v99, v110
	v_mul_f32_e32 v107, v107, v160
	v_mul_f32_e32 v113, v113, v161
	v_mul_f32_e32 v102, v102, v103
	v_mul_f32_e32 v103, v98, v99
	v_mul_f32_e32 v98, v105, v109
	v_mul_f32_e32 v106, v106, v107
	v_mul_f32_e32 v107, v112, v113
	v_mul_f32_e32 v104, v104, v98
	v_cvt_pk_bf16_f32 v98, v100, v101
	v_cvt_pk_bf16_f32 v99, v106, v107
	v_cvt_pk_bf16_f32 v100, v108, v102
	v_cvt_pk_bf16_f32 v101, v103, v104
	v_mad_i64_i32 v[102:103], s[0:1], v158, s71, v[152:153]
	v_lshl_add_u64 v[102:103], v[102:103], 0, v[154:155]
	global_store_dwordx4 v[102:103], v[98:101], off
	v_cvt_f32_i32_e32 v103, v94
	v_cvt_f32_i32_e32 v102, v90
	v_or_b32_e32 v98, 32, v148
	v_ashrrev_i32_e32 v99, 31, v98
	v_lshl_add_u64 v[100:101], v[98:99], 2, s[26:27]
	s_nop 1
	v_cvt_f32_i32_e32 v94, v91
	v_cvt_f32_i32_e32 v91, v96
	v_cvt_f32_i32_e32 v90, v92
	v_cvt_f32_i32_e32 v96, v93
	v_cvt_f32_i32_e32 v93, v86
	v_cvt_f32_i32_e32 v92, v82
	v_cvt_f32_i32_e32 v86, v83
	v_cvt_f32_i32_e32 v83, v88
	v_cvt_f32_i32_e32 v82, v84
	v_cvt_f32_i32_e32 v88, v85
	v_mov_b32_e32 v100, v194
	v_pk_mul_f32 v[110:111], v[126:127], v[100:101] op_sel_hi:[1,0]
	v_pk_mul_f32 v[84:85], v[122:123], v[100:101] op_sel_hi:[1,0]
	v_pk_mul_f32 v[92:93], v[110:111], v[92:93]
	v_pk_mul_f32 v[84:85], v[84:85], v[102:103]
	v_exp_f32_e64 v103, -v93
	v_pk_mul_f32 v[104:105], v[120:121], v[100:101] op_sel_hi:[1,0]
	v_pk_mul_f32 v[112:113], v[118:119], v[100:101] op_sel_hi:[1,0]
	v_pk_mul_f32 v[158:159], v[128:129], v[100:101] op_sel_hi:[1,0]
	v_pk_mul_f32 v[106:107], v[124:125], v[100:101] op_sel_hi:[1,0]
	v_pk_mul_f32 v[108:109], v[116:117], v[100:101] op_sel_hi:[1,0]
	v_pk_mul_f32 v[100:101], v[114:115], v[100:101] op_sel_hi:[1,0]
	v_pk_mul_f32 v[94:95], v[104:105], v[94:95]
	v_pk_mul_f32 v[86:87], v[112:113], v[86:87]
	v_pk_mul_f32 v[82:83], v[158:159], v[82:83]
	v_pk_mul_f32 v[90:91], v[106:107], v[90:91]
	v_pk_mul_f32 v[96:97], v[108:109], v[96:97]
	v_pk_mul_f32 v[88:89], v[100:101], v[88:89]
	v_add_f32_e32 v103, 1.0, v103
	v_exp_f32_e64 v99, -v85
	v_exp_f32_e64 v100, -v95
	v_exp_f32_e64 v104, -v87
	v_exp_f32_e64 v105, -v83
	v_rcp_f32_e32 v103, v103
	v_exp_f32_e64 v101, -v91
	v_exp_f32_e64 v102, -v97
	v_exp_f32_e64 v106, -v89
	v_add_f32_e32 v99, 1.0, v99
	v_add_f32_e32 v100, 1.0, v100
	v_add_f32_e32 v104, 1.0, v104
	v_add_f32_e32 v105, 1.0, v105
	v_mul_f32_e32 v93, v93, v103
	v_add_f32_e32 v101, 1.0, v101
	v_add_f32_e32 v102, 1.0, v102
	v_rcp_f32_e32 v99, v99
	v_rcp_f32_e32 v100, v100
	v_rcp_f32_e32 v104, v104
	v_rcp_f32_e32 v105, v105
	v_mul_f32_e32 v92, v92, v93
	v_add_f32_e32 v93, 1.0, v106
	v_rcp_f32_e32 v101, v101
	v_rcp_f32_e32 v102, v102
	v_rcp_f32_e32 v93, v93
	v_mul_f32_e32 v85, v85, v99
	v_mul_f32_e32 v95, v95, v100
	v_mul_f32_e32 v87, v87, v104
	v_mul_f32_e32 v83, v83, v105
	v_mul_f32_e32 v91, v91, v101
	v_mul_f32_e32 v97, v97, v102
	v_mul_f32_e32 v84, v84, v85
	v_mul_f32_e32 v85, v94, v95
	v_mul_f32_e32 v86, v86, v87
	v_mul_f32_e32 v87, v82, v83
	v_mul_f32_e32 v82, v89, v93
	v_mul_f32_e32 v90, v90, v91
	v_mul_f32_e32 v91, v96, v97
	v_mul_f32_e32 v88, v88, v82
	v_cvt_pk_bf16_f32 v82, v84, v85
	v_cvt_pk_bf16_f32 v83, v90, v91
	v_cvt_pk_bf16_f32 v84, v92, v86
	v_cvt_pk_bf16_f32 v85, v87, v88
	v_mad_i64_i32 v[86:87], s[0:1], v98, s71, v[152:153]
	v_lshl_add_u64 v[86:87], v[86:87], 0, v[154:155]
	global_store_dwordx4 v[86:87], v[82:85], off
	v_cvt_f32_i32_e32 v87, v78
	v_cvt_f32_i32_e32 v86, v74
	v_or_b32_e32 v82, 48, v148
	v_ashrrev_i32_e32 v83, 31, v82
	v_lshl_add_u64 v[84:85], v[82:83], 2, s[26:27]
	s_nop 1
	v_cvt_f32_i32_e32 v78, v75
	v_cvt_f32_i32_e32 v75, v80
	v_cvt_f32_i32_e32 v74, v76
	v_cvt_f32_i32_e32 v80, v77
	v_cvt_f32_i32_e32 v77, v70
	v_cvt_f32_i32_e32 v76, v66
	v_cvt_f32_i32_e32 v70, v67
	v_cvt_f32_i32_e32 v67, v72
	v_cvt_f32_i32_e32 v66, v68
	v_cvt_f32_i32_e32 v72, v69
	v_mov_b32_e32 v84, v196
	v_pk_mul_f32 v[68:69], v[122:123], v[84:85] op_sel_hi:[1,0]
	v_pk_mul_f32 v[88:89], v[120:121], v[84:85] op_sel_hi:[1,0]
	v_pk_mul_f32 v[96:97], v[118:119], v[84:85] op_sel_hi:[1,0]
	v_pk_mul_f32 v[98:99], v[128:129], v[84:85] op_sel_hi:[1,0]
	v_pk_mul_f32 v[90:91], v[124:125], v[84:85] op_sel_hi:[1,0]
	v_pk_mul_f32 v[92:93], v[116:117], v[84:85] op_sel_hi:[1,0]
	v_pk_mul_f32 v[94:95], v[126:127], v[84:85] op_sel_hi:[1,0]
	v_pk_mul_f32 v[84:85], v[114:115], v[84:85] op_sel_hi:[1,0]
	v_pk_mul_f32 v[68:69], v[68:69], v[86:87]
	v_pk_mul_f32 v[78:79], v[88:89], v[78:79]
	v_pk_mul_f32 v[70:71], v[96:97], v[70:71]
	v_pk_mul_f32 v[66:67], v[98:99], v[66:67]
	v_pk_mul_f32 v[74:75], v[90:91], v[74:75]
	v_pk_mul_f32 v[80:81], v[92:93], v[80:81]
	v_pk_mul_f32 v[76:77], v[94:95], v[76:77]
	v_pk_mul_f32 v[72:73], v[84:85], v[72:73]
	v_exp_f32_e64 v83, -v69
	v_exp_f32_e64 v84, -v79
	v_exp_f32_e64 v88, -v71
	v_exp_f32_e64 v89, -v67
	v_exp_f32_e64 v85, -v75
	v_exp_f32_e64 v86, -v81
	v_exp_f32_e64 v87, -v77
	v_exp_f32_e64 v90, -v73
	v_add_f32_e32 v83, 1.0, v83
	v_add_f32_e32 v84, 1.0, v84
	v_add_f32_e32 v88, 1.0, v88
	v_add_f32_e32 v89, 1.0, v89
	v_add_f32_e32 v85, 1.0, v85
	v_add_f32_e32 v86, 1.0, v86
	v_add_f32_e32 v87, 1.0, v87
	v_add_f32_e32 v90, 1.0, v90
	v_rcp_f32_e32 v83, v83
	v_rcp_f32_e32 v84, v84
	v_rcp_f32_e32 v88, v88
	v_rcp_f32_e32 v89, v89
	v_rcp_f32_e32 v85, v85
	v_rcp_f32_e32 v86, v86
	v_rcp_f32_e32 v87, v87
	v_rcp_f32_e32 v90, v90
	v_mul_f32_e32 v69, v69, v83
	v_mul_f32_e32 v79, v79, v84
	v_mul_f32_e32 v71, v71, v88
	v_mul_f32_e32 v67, v67, v89
	v_mul_f32_e32 v75, v75, v85
	v_mul_f32_e32 v81, v81, v86
	v_mul_f32_e32 v77, v77, v87
	v_mul_f32_e32 v68, v68, v69
	v_mul_f32_e32 v69, v78, v79
	v_mul_f32_e32 v70, v70, v71
	v_mul_f32_e32 v71, v66, v67
	v_mul_f32_e32 v66, v73, v90
	v_mul_f32_e32 v74, v74, v75
	v_mul_f32_e32 v75, v80, v81
	v_mul_f32_e32 v76, v76, v77
	v_mul_f32_e32 v72, v72, v66
	v_cvt_pk_bf16_f32 v66, v68, v69
	v_cvt_pk_bf16_f32 v67, v74, v75
	v_cvt_pk_bf16_f32 v68, v76, v70
	v_cvt_pk_bf16_f32 v69, v71, v72
	v_mad_i64_i32 v[70:71], s[0:1], v82, s71, v[152:153]
	v_lshl_add_u64 v[70:71], v[70:71], 0, v[154:155]
	global_store_dwordx4 v[70:71], v[66:69], off
	s_nop 1
	v_add_u32_e32 v82, 0x80, v148
	v_cvt_f32_i32_e32 v69, v62
	v_cvt_f32_i32_e32 v68, v58
	v_cvt_f32_i32_e32 v62, v59
	v_cvt_f32_i32_e32 v59, v64
	v_cvt_f32_i32_e32 v58, v60
	v_cvt_f32_i32_e32 v64, v61
	v_cvt_f32_i32_e32 v61, v54
	v_cvt_f32_i32_e32 v60, v50
	v_cvt_f32_i32_e32 v54, v51
	v_cvt_f32_i32_e32 v51, v56
	v_cvt_f32_i32_e32 v50, v52
	v_cvt_f32_i32_e32 v56, v53
	v_mov_b32_e32 v66, v198
	v_pk_mul_f32 v[52:53], v[122:123], v[66:67] op_sel_hi:[1,0]
	v_pk_mul_f32 v[70:71], v[120:121], v[66:67] op_sel_hi:[1,0]
	v_pk_mul_f32 v[78:79], v[118:119], v[66:67] op_sel_hi:[1,0]
	v_pk_mul_f32 v[80:81], v[128:129], v[66:67] op_sel_hi:[1,0]
	v_pk_mul_f32 v[72:73], v[124:125], v[66:67] op_sel_hi:[1,0]
	v_pk_mul_f32 v[74:75], v[116:117], v[66:67] op_sel_hi:[1,0]
	v_pk_mul_f32 v[76:77], v[126:127], v[66:67] op_sel_hi:[1,0]
	v_pk_mul_f32 v[66:67], v[114:115], v[66:67] op_sel_hi:[1,0]
	v_pk_mul_f32 v[52:53], v[52:53], v[68:69]
	v_pk_mul_f32 v[62:63], v[70:71], v[62:63]
	v_pk_mul_f32 v[54:55], v[78:79], v[54:55]
	v_pk_mul_f32 v[50:51], v[80:81], v[50:51]
	v_pk_mul_f32 v[58:59], v[72:73], v[58:59]
	v_pk_mul_f32 v[64:65], v[74:75], v[64:65]
	v_pk_mul_f32 v[60:61], v[76:77], v[60:61]
	v_pk_mul_f32 v[56:57], v[66:67], v[56:57]
	v_exp_f32_e64 v66, -v53
	v_exp_f32_e64 v67, -v63
	v_exp_f32_e64 v71, -v55
	v_exp_f32_e64 v72, -v51
	v_exp_f32_e64 v68, -v59
	v_exp_f32_e64 v69, -v65
	v_exp_f32_e64 v70, -v61
	v_exp_f32_e64 v73, -v57
	v_add_f32_e32 v66, 1.0, v66
	v_add_f32_e32 v67, 1.0, v67
	v_add_f32_e32 v71, 1.0, v71
	v_add_f32_e32 v72, 1.0, v72
	v_add_f32_e32 v68, 1.0, v68
	v_add_f32_e32 v69, 1.0, v69
	v_add_f32_e32 v70, 1.0, v70
	v_add_f32_e32 v73, 1.0, v73
	v_rcp_f32_e32 v66, v66
	v_rcp_f32_e32 v67, v67
	v_rcp_f32_e32 v71, v71
	v_rcp_f32_e32 v72, v72
	v_rcp_f32_e32 v68, v68
	v_rcp_f32_e32 v69, v69
	v_rcp_f32_e32 v70, v70
	v_rcp_f32_e32 v73, v73
	v_mul_f32_e32 v53, v53, v66
	v_mul_f32_e32 v63, v63, v67
	v_mul_f32_e32 v55, v55, v71
	v_mul_f32_e32 v51, v51, v72
	v_mul_f32_e32 v59, v59, v68
	v_mul_f32_e32 v65, v65, v69
	v_mul_f32_e32 v61, v61, v70
	v_mul_f32_e32 v57, v57, v73
	v_mul_f32_e32 v52, v52, v53
	v_mul_f32_e32 v53, v62, v63
	v_mul_f32_e32 v54, v54, v55
	v_mul_f32_e32 v55, v50, v51
	v_mul_f32_e32 v58, v58, v59
	v_mul_f32_e32 v59, v64, v65
	v_mul_f32_e32 v60, v60, v61
	v_mul_f32_e32 v56, v56, v57
	v_cvt_pk_bf16_f32 v50, v52, v53
	v_cvt_pk_bf16_f32 v51, v58, v59
	v_cvt_pk_bf16_f32 v52, v60, v54
	v_cvt_pk_bf16_f32 v53, v55, v56
	v_mad_i64_i32 v[54:55], s[0:1], v82, s71, v[152:153]
	v_lshl_add_u64 v[54:55], v[54:55], 0, v[154:155]
	global_store_dwordx4 v[54:55], v[50:53], off
	s_nop 1
	v_mov_b32_e32 v50, v200
	v_pk_mul_f32 v[56:57], v[120:121], v[50:51] op_sel_hi:[1,0]
	v_cvt_f32_i32_e32 v53, v46
	v_cvt_f32_i32_e32 v52, v42
	v_cvt_f32_i32_e32 v46, v43
	v_cvt_f32_i32_e32 v43, v48
	v_cvt_f32_i32_e32 v42, v44
	v_cvt_f32_i32_e32 v48, v45
	v_cvt_f32_i32_e32 v45, v38
	v_cvt_f32_i32_e32 v44, v34
	v_cvt_f32_i32_e32 v38, v35
	v_cvt_f32_i32_e32 v35, v40
	v_cvt_f32_i32_e32 v34, v36
	v_cvt_f32_i32_e32 v40, v37
	v_add_u32_e32 v36, 0x90, v148
	v_mad_i64_i32 v[36:37], s[0:1], v36, s71, v[152:153]
	v_lshl_add_u64 v[54:55], v[36:37], 0, v[154:155]
	v_pk_mul_f32 v[36:37], v[122:123], v[50:51] op_sel_hi:[1,0]
	v_pk_mul_f32 v[58:59], v[124:125], v[50:51] op_sel_hi:[1,0]
	v_pk_mul_f32 v[60:61], v[116:117], v[50:51] op_sel_hi:[1,0]
	v_pk_mul_f32 v[62:63], v[126:127], v[50:51] op_sel_hi:[1,0]
	v_pk_mul_f32 v[64:65], v[118:119], v[50:51] op_sel_hi:[1,0]
	v_pk_mul_f32 v[66:67], v[128:129], v[50:51] op_sel_hi:[1,0]
	v_pk_mul_f32 v[50:51], v[114:115], v[50:51] op_sel_hi:[1,0]
	v_pk_mul_f32 v[36:37], v[36:37], v[52:53]
	v_pk_mul_f32 v[46:47], v[56:57], v[46:47]
	v_pk_mul_f32 v[42:43], v[58:59], v[42:43]
	v_pk_mul_f32 v[48:49], v[60:61], v[48:49]
	v_pk_mul_f32 v[44:45], v[62:63], v[44:45]
	v_pk_mul_f32 v[38:39], v[64:65], v[38:39]
	v_pk_mul_f32 v[34:35], v[66:67], v[34:35]
	v_pk_mul_f32 v[40:41], v[50:51], v[40:41]
	v_exp_f32_e64 v50, -v37
	v_exp_f32_e64 v51, -v47
	v_exp_f32_e64 v52, -v43
	v_exp_f32_e64 v53, -v49
	v_exp_f32_e64 v56, -v45
	v_exp_f32_e64 v57, -v39
	v_exp_f32_e64 v58, -v35
	v_exp_f32_e64 v59, -v41
	v_add_f32_e32 v50, 1.0, v50
	v_add_f32_e32 v51, 1.0, v51
	v_add_f32_e32 v52, 1.0, v52
	v_add_f32_e32 v53, 1.0, v53
	v_add_f32_e32 v56, 1.0, v56
	v_add_f32_e32 v57, 1.0, v57
	v_add_f32_e32 v58, 1.0, v58
	v_add_f32_e32 v59, 1.0, v59
	v_rcp_f32_e32 v50, v50
	v_rcp_f32_e32 v51, v51
	v_rcp_f32_e32 v52, v52
	v_rcp_f32_e32 v53, v53
	v_rcp_f32_e32 v56, v56
	v_rcp_f32_e32 v57, v57
	v_rcp_f32_e32 v58, v58
	v_rcp_f32_e32 v59, v59
	v_mul_f32_e32 v37, v37, v50
	v_mul_f32_e32 v47, v47, v51
	v_mul_f32_e32 v43, v43, v52
	v_mul_f32_e32 v49, v49, v53
	v_mul_f32_e32 v45, v45, v56
	v_mul_f32_e32 v39, v39, v57
	v_mul_f32_e32 v35, v35, v58
	v_mul_f32_e32 v41, v41, v59
	v_mul_f32_e32 v36, v36, v37
	v_mul_f32_e32 v37, v46, v47
	v_mul_f32_e32 v42, v42, v43
	v_mul_f32_e32 v43, v48, v49
	v_mul_f32_e32 v44, v44, v45
	v_mul_f32_e32 v38, v38, v39
	v_mul_f32_e32 v39, v34, v35
	v_mul_f32_e32 v40, v40, v41
	v_cvt_pk_bf16_f32 v34, v36, v37
	v_cvt_pk_bf16_f32 v35, v42, v43
	v_cvt_pk_bf16_f32 v36, v44, v38
	v_cvt_pk_bf16_f32 v37, v39, v40
	global_store_dwordx4 v[54:55], v[34:37], off
	s_nop 1
	v_mov_b32_e32 v34, v202
	v_pk_mul_f32 v[40:41], v[120:121], v[34:35] op_sel_hi:[1,0]
	v_cvt_f32_i32_e32 v37, v30
	v_cvt_f32_i32_e32 v36, v26
	v_cvt_f32_i32_e32 v30, v27
	v_cvt_f32_i32_e32 v27, v32
	v_cvt_f32_i32_e32 v26, v28
	v_cvt_f32_i32_e32 v32, v29
	v_cvt_f32_i32_e32 v29, v22
	v_cvt_f32_i32_e32 v28, v18
	v_cvt_f32_i32_e32 v22, v19
	v_cvt_f32_i32_e32 v19, v24
	v_cvt_f32_i32_e32 v18, v20
	v_cvt_f32_i32_e32 v24, v21
	v_add_u32_e32 v20, 0xa0, v148
	v_mad_i64_i32 v[20:21], s[0:1], v20, s71, v[152:153]
	v_lshl_add_u64 v[38:39], v[20:21], 0, v[154:155]
	v_pk_mul_f32 v[20:21], v[122:123], v[34:35] op_sel_hi:[1,0]
	v_pk_mul_f32 v[42:43], v[124:125], v[34:35] op_sel_hi:[1,0]
	v_pk_mul_f32 v[44:45], v[116:117], v[34:35] op_sel_hi:[1,0]
	v_pk_mul_f32 v[46:47], v[126:127], v[34:35] op_sel_hi:[1,0]
	v_pk_mul_f32 v[48:49], v[118:119], v[34:35] op_sel_hi:[1,0]
	v_pk_mul_f32 v[50:51], v[128:129], v[34:35] op_sel_hi:[1,0]
	v_pk_mul_f32 v[34:35], v[114:115], v[34:35] op_sel_hi:[1,0]
	v_pk_mul_f32 v[20:21], v[20:21], v[36:37]
	v_pk_mul_f32 v[30:31], v[40:41], v[30:31]
	v_pk_mul_f32 v[26:27], v[42:43], v[26:27]
	v_pk_mul_f32 v[32:33], v[44:45], v[32:33]
	v_pk_mul_f32 v[28:29], v[46:47], v[28:29]
	v_pk_mul_f32 v[22:23], v[48:49], v[22:23]
	v_pk_mul_f32 v[18:19], v[50:51], v[18:19]
	v_pk_mul_f32 v[24:25], v[34:35], v[24:25]
	v_exp_f32_e64 v34, -v21
	v_exp_f32_e64 v35, -v31
	v_exp_f32_e64 v36, -v27
	v_exp_f32_e64 v37, -v33
	v_exp_f32_e64 v40, -v29
	v_exp_f32_e64 v41, -v23
	v_exp_f32_e64 v42, -v19
	v_exp_f32_e64 v43, -v25
	v_add_f32_e32 v34, 1.0, v34
	v_add_f32_e32 v35, 1.0, v35
	v_add_f32_e32 v36, 1.0, v36
	v_add_f32_e32 v37, 1.0, v37
	v_add_f32_e32 v40, 1.0, v40
	v_add_f32_e32 v41, 1.0, v41
	v_add_f32_e32 v42, 1.0, v42
	v_add_f32_e32 v43, 1.0, v43
	v_rcp_f32_e32 v34, v34
	v_rcp_f32_e32 v35, v35
	v_rcp_f32_e32 v36, v36
	v_rcp_f32_e32 v37, v37
	v_rcp_f32_e32 v40, v40
	v_rcp_f32_e32 v41, v41
	v_rcp_f32_e32 v42, v42
	v_rcp_f32_e32 v43, v43
	v_mul_f32_e32 v21, v21, v34
	v_mul_f32_e32 v31, v31, v35
	v_mul_f32_e32 v27, v27, v36
	v_mul_f32_e32 v33, v33, v37
	v_mul_f32_e32 v29, v29, v40
	v_mul_f32_e32 v23, v23, v41
	v_mul_f32_e32 v19, v19, v42
	v_mul_f32_e32 v25, v25, v43
	v_mul_f32_e32 v20, v20, v21
	v_mul_f32_e32 v21, v30, v31
	v_mul_f32_e32 v26, v26, v27
	v_mul_f32_e32 v27, v32, v33
	v_mul_f32_e32 v28, v28, v29
	v_mul_f32_e32 v22, v22, v23
	v_mul_f32_e32 v23, v18, v19
	v_mul_f32_e32 v24, v24, v25
	v_cvt_pk_bf16_f32 v18, v20, v21
	v_cvt_pk_bf16_f32 v19, v26, v27
	v_cvt_pk_bf16_f32 v20, v28, v22
	v_cvt_pk_bf16_f32 v21, v23, v24
	global_store_dwordx4 v[38:39], v[18:21], off
	s_nop 1
	v_mov_b32_e32 v18, v204
	v_pk_mul_f32 v[24:25], v[120:121], v[18:19] op_sel_hi:[1,0]
	v_cvt_f32_i32_e32 v21, v14
	v_cvt_f32_i32_e32 v20, v10
	v_cvt_f32_i32_e32 v14, v11
	v_cvt_f32_i32_e32 v11, v16
	v_cvt_f32_i32_e32 v10, v12
	v_cvt_f32_i32_e32 v16, v13
	v_cvt_f32_i32_e32 v13, v6
	v_cvt_f32_i32_e32 v12, v2
	v_cvt_f32_i32_e32 v6, v3
	v_cvt_f32_i32_e32 v3, v8
	v_cvt_f32_i32_e32 v2, v4
	v_cvt_f32_i32_e32 v8, v5
	v_add_u32_e32 v4, 0xb0, v148
	v_mad_i64_i32 v[4:5], s[0:1], v4, s71, v[152:153]
	v_lshl_add_u64 v[22:23], v[4:5], 0, v[154:155]
	v_pk_mul_f32 v[4:5], v[122:123], v[18:19] op_sel_hi:[1,0]
	v_pk_mul_f32 v[26:27], v[124:125], v[18:19] op_sel_hi:[1,0]
	v_pk_mul_f32 v[28:29], v[116:117], v[18:19] op_sel_hi:[1,0]
	v_pk_mul_f32 v[30:31], v[126:127], v[18:19] op_sel_hi:[1,0]
	v_pk_mul_f32 v[32:33], v[118:119], v[18:19] op_sel_hi:[1,0]
	v_pk_mul_f32 v[34:35], v[128:129], v[18:19] op_sel_hi:[1,0]
	v_pk_mul_f32 v[18:19], v[114:115], v[18:19] op_sel_hi:[1,0]
	v_pk_mul_f32 v[4:5], v[4:5], v[20:21]
	v_pk_mul_f32 v[14:15], v[24:25], v[14:15]
	v_pk_mul_f32 v[10:11], v[26:27], v[10:11]
	v_pk_mul_f32 v[16:17], v[28:29], v[16:17]
	v_pk_mul_f32 v[12:13], v[30:31], v[12:13]
	v_pk_mul_f32 v[6:7], v[32:33], v[6:7]
	v_pk_mul_f32 v[2:3], v[34:35], v[2:3]
	v_pk_mul_f32 v[8:9], v[18:19], v[8:9]
	v_exp_f32_e64 v18, -v5
	v_exp_f32_e64 v19, -v15
	v_exp_f32_e64 v20, -v11
	v_exp_f32_e64 v21, -v17
	v_exp_f32_e64 v24, -v13
	v_exp_f32_e64 v25, -v7
	v_exp_f32_e64 v26, -v3
	v_exp_f32_e64 v27, -v9
	v_add_f32_e32 v18, 1.0, v18
	v_add_f32_e32 v19, 1.0, v19
	v_add_f32_e32 v20, 1.0, v20
	v_add_f32_e32 v21, 1.0, v21
	v_add_f32_e32 v24, 1.0, v24
	v_add_f32_e32 v25, 1.0, v25
	v_add_f32_e32 v26, 1.0, v26
	v_add_f32_e32 v27, 1.0, v27
	v_rcp_f32_e32 v18, v18
	v_rcp_f32_e32 v19, v19
	v_rcp_f32_e32 v20, v20
	v_rcp_f32_e32 v21, v21
	v_rcp_f32_e32 v24, v24
	v_rcp_f32_e32 v25, v25
	v_rcp_f32_e32 v26, v26
	v_rcp_f32_e32 v27, v27
	v_mul_f32_e32 v5, v5, v18
	v_mul_f32_e32 v15, v15, v19
	v_mul_f32_e32 v11, v11, v20
	v_mul_f32_e32 v17, v17, v21
	v_mul_f32_e32 v13, v13, v24
	v_mul_f32_e32 v7, v7, v25
	v_mul_f32_e32 v3, v3, v26
	v_mul_f32_e32 v9, v9, v27
	v_mul_f32_e32 v4, v4, v5
	v_mul_f32_e32 v5, v14, v15
	s_mov_b64 s[0:1], -1
	v_mul_f32_e32 v10, v10, v11
	v_mul_f32_e32 v11, v16, v17
	v_mul_f32_e32 v12, v12, v13
	v_mul_f32_e32 v6, v6, v7
	v_mul_f32_e32 v7, v2, v3
	v_mul_f32_e32 v8, v8, v9
	v_cvt_pk_bf16_f32 v2, v4, v5
	v_cvt_pk_bf16_f32 v3, v10, v11
	v_cvt_pk_bf16_f32 v4, v12, v6
	v_cvt_pk_bf16_f32 v5, v7, v8
	global_store_dwordx4 v[22:23], v[2:5], off
	s_cbranch_vccnz .LBB0_188
	s_andn2_b64 vcc, exec, s[20:21]
	s_cbranch_vccnz .LBB0_187
	s_barrier
	s_branch .LBB0_187

.LBB0_613:
	v_lshl_or_b32 v156, s67, 8, v162
	v_ashrrev_i32_e32 v157, 31, v156
	v_lshl_add_u32 v152, s48, 8, v1
	v_lshl_add_u64 v[150:151], v[156:157], 2, s[18:19]
	v_ashrrev_i32_e32 v153, 31, v152
	global_load_dwordx4 v[166:169], v[150:151], off offset:16
	global_load_dwordx4 v[158:161], v[150:151], off
	v_lshl_add_u64 v[148:149], v[152:153], 2, s[26:27]
	global_load_dword v153, v[148:149], off
	global_load_dword v190, v[148:149], off
	global_load_dword v192, v[148:149], off offset:64
	global_load_dword v194, v[148:149], off offset:128
	global_load_dword v196, v[148:149], off offset:192
	global_load_dword v198, v[148:149], off offset:512
	global_load_dword v200, v[148:149], off offset:576
	global_load_dword v202, v[148:149], off offset:640
	global_load_dword v204, v[148:149], off offset:704
	global_load_dwordx4 v[206:209], v[150:151], off offset:512
	global_load_dwordx4 v[210:213], v[150:151], off offset:528
	v_cvt_f32_i32_e32 v172, v126
	v_cvt_f32_i32_e32 v173, v127
	v_cvt_f32_i32_e32 v174, v128
	v_cvt_f32_i32_e32 v175, v129
	v_cvt_f32_i32_e32 v176, v122
	v_cvt_f32_i32_e32 v177, v123
	v_cvt_f32_i32_e32 v178, v124
	v_cvt_f32_i32_e32 v179, v125
	v_or_b32_e32 v170, 16, v152
	v_lshlrev_b64 v[128:129], 1, v[156:157]
	v_ashrrev_i32_e32 v171, 31, v170
	v_lshl_add_u64 v[124:125], v[170:171], 2, s[26:27]
	s_cmp_lt_i32 s67, 0
	v_mov_b64_e32 v[154:155], s[16:17]
	v_mad_i64_i32 v[122:123], s[0:1], v152, s65, v[154:155]
	s_cselect_b64 s[6:7], -1, 0
	v_lshl_add_u64 v[122:123], v[122:123], 0, v[128:129]
	v_cvt_f32_i32_e32 v118, v118
	v_cvt_f32_i32_e32 v119, v119
	v_cvt_f32_i32_e32 v120, v120
	v_cvt_f32_i32_e32 v121, v121
	v_cvt_f32_i32_e32 v110, v110
	v_cvt_f32_i32_e32 v111, v111
	v_cvt_f32_i32_e32 v112, v112
	v_cvt_f32_i32_e32 v113, v113
	v_cvt_f32_i32_e32 v102, v102
	v_cvt_f32_i32_e32 v103, v103
	v_cvt_f32_i32_e32 v104, v104
	v_cvt_f32_i32_e32 v105, v105
	v_cvt_f32_i32_e32 v100, v100
	v_cvt_f32_i32_e32 v101, v101
	v_cvt_f32_i32_e32 v94, v94
	v_cvt_f32_i32_e32 v95, v95
	v_cvt_f32_i32_e32 v96, v96
	v_cvt_f32_i32_e32 v97, v97
	v_cvt_f32_i32_e32 v92, v92
	v_cvt_f32_i32_e32 v93, v93
	v_cvt_f32_i32_e32 v86, v86
	v_cvt_f32_i32_e32 v87, v87
	v_cvt_f32_i32_e32 v88, v88
	v_cvt_f32_i32_e32 v89, v89
	v_cvt_f32_i32_e32 v84, v84
	v_cvt_f32_i32_e32 v85, v85
	v_cvt_f32_i32_e32 v78, v78
	v_cvt_f32_i32_e32 v79, v79
	v_cvt_f32_i32_e32 v80, v80
	v_cvt_f32_i32_e32 v81, v81
	v_cvt_f32_i32_e32 v76, v76
	v_cvt_f32_i32_e32 v77, v77
	v_cvt_f32_i32_e32 v70, v70
	v_cvt_f32_i32_e32 v71, v71
	v_cvt_f32_i32_e32 v72, v72
	v_cvt_f32_i32_e32 v73, v73
	v_cvt_f32_i32_e32 v68, v68
	v_cvt_f32_i32_e32 v69, v69
	v_cvt_f32_i32_e32 v53, v53
	v_cvt_f32_i32_e32 v54, v54
	v_cvt_f32_i32_e32 v55, v55
	v_cvt_f32_i32_e32 v56, v56
	v_cvt_f32_i32_e32 v57, v57
	v_cvt_f32_i32_e32 v50, v50
	v_cvt_f32_i32_e32 v51, v51
	v_cvt_f32_i32_e32 v52, v52
	v_cvt_f32_i32_e32 v45, v45
	v_cvt_f32_i32_e32 v46, v46
	v_cvt_f32_i32_e32 v47, v47
	v_cvt_f32_i32_e32 v48, v48
	v_cvt_f32_i32_e32 v49, v49
	v_cvt_f32_i32_e32 v42, v42
	v_cvt_f32_i32_e32 v43, v43
	v_cvt_f32_i32_e32 v44, v44
	v_cvt_f32_i32_e32 v37, v37
	v_cvt_f32_i32_e32 v38, v38
	v_cvt_f32_i32_e32 v39, v39
	v_cvt_f32_i32_e32 v40, v40
	s_waitcnt vmcnt(0)
	s_mov_b32 s98, 0x3c3a1e78
	v_pk_mul_f32 v[126:127], v[168:169], s[98:99] op_sel_hi:[1,0]
	v_pk_mul_f32 v[156:157], v[160:161], s[98:99] op_sel_hi:[1,0]
	v_pk_mul_f32 v[160:161], v[158:159], s[98:99] op_sel_hi:[1,0]
	v_pk_mul_f32 v[158:159], v[166:167], s[98:99] op_sel_hi:[1,0]
	v_mul_f32_e32 v166, v160, v153
	v_mul_f32_e32 v167, v161, v153
	v_mul_f32_e32 v168, v156, v153
	v_mul_f32_e32 v169, v157, v153
	v_mul_f32_e32 v171, v153, v158
	v_mul_f32_e32 v180, v153, v159
	v_mul_f32_e32 v181, v153, v126
	v_mul_f32_e32 v153, v153, v127
	v_mul_f32_e32 v166, v166, v172
	v_mul_f32_e32 v167, v167, v173
	v_mul_f32_e32 v168, v168, v174
	v_mul_f32_e32 v169, v169, v175
	v_mul_f32_e32 v171, v171, v176
	v_mul_f32_e32 v172, v180, v177
	v_mul_f32_e32 v173, v181, v178
	v_mul_f32_e32 v153, v153, v179
	v_exp_f32_e64 v174, -v166
	v_exp_f32_e64 v175, -v167
	v_exp_f32_e64 v176, -v168
	v_exp_f32_e64 v177, -v169
	v_exp_f32_e64 v178, -v171
	v_exp_f32_e64 v179, -v172
	v_exp_f32_e64 v180, -v173
	v_exp_f32_e64 v181, -v153
	v_add_f32_e32 v174, 1.0, v174
	v_add_f32_e32 v175, 1.0, v175
	v_add_f32_e32 v176, 1.0, v176
	v_add_f32_e32 v177, 1.0, v177
	v_add_f32_e32 v178, 1.0, v178
	v_add_f32_e32 v179, 1.0, v179
	v_add_f32_e32 v180, 1.0, v180
	v_add_f32_e32 v181, 1.0, v181
	v_rcp_f32_e32 v174, v174
	v_rcp_f32_e32 v175, v175
	v_rcp_f32_e32 v176, v176
	v_rcp_f32_e32 v177, v177
	v_rcp_f32_e32 v178, v178
	v_rcp_f32_e32 v179, v179
	v_rcp_f32_e32 v180, v180
	v_rcp_f32_e32 v181, v181
	v_cvt_pk_bf16_f32 v166, v174, v175
	v_cvt_pk_bf16_f32 v167, v176, v177
	v_cvt_pk_bf16_f32 v168, v178, v179
	v_cvt_pk_bf16_f32 v169, v180, v181
	global_store_dwordx4 v[122:123], v[166:169], off
	s_nop 1
	v_cvt_f32_i32_e32 v171, v116
	v_cvt_f32_i32_e32 v168, v114
	v_cvt_f32_i32_e32 v169, v115
	v_cvt_f32_i32_e32 v172, v117
	v_or_b32_e32 v166, 32, v152
	v_ashrrev_i32_e32 v167, 31, v166
	v_mad_i64_i32 v[114:115], s[0:1], v170, s65, v[154:155]
	v_lshl_add_u64 v[116:117], v[166:167], 2, s[26:27]
	v_lshl_add_u64 v[114:115], v[114:115], 0, v[128:129]
	v_cvt_f32_i32_e32 v41, v41
	v_cvt_f32_i32_e32 v34, v34
	v_cvt_f32_i32_e32 v35, v35
	v_cvt_f32_i32_e32 v36, v36
	v_cvt_f32_i32_e32 v29, v29
	v_cvt_f32_i32_e32 v30, v30
	v_cvt_f32_i32_e32 v31, v31
	v_cvt_f32_i32_e32 v32, v32
	v_cvt_f32_i32_e32 v33, v33
	v_cvt_f32_i32_e32 v26, v26
	v_cvt_f32_i32_e32 v27, v27
	v_cvt_f32_i32_e32 v28, v28
	v_cvt_f32_i32_e32 v21, v21
	v_cvt_f32_i32_e32 v22, v22
	v_cvt_f32_i32_e32 v23, v23
	v_cvt_f32_i32_e32 v24, v24
	v_cvt_f32_i32_e32 v25, v25
	v_cvt_f32_i32_e32 v18, v18
	v_cvt_f32_i32_e32 v19, v19
	v_cvt_f32_i32_e32 v20, v20
	v_cvt_f32_i32_e32 v13, v13
	v_cvt_f32_i32_e32 v14, v14
	v_cvt_f32_i32_e32 v15, v15
	v_cvt_f32_i32_e32 v16, v16
	v_cvt_f32_i32_e32 v17, v17
	v_cvt_f32_i32_e32 v10, v10
	v_cvt_f32_i32_e32 v11, v11
	v_cvt_f32_i32_e32 v12, v12
	v_cvt_f32_i32_e32 v5, v5
	v_cvt_f32_i32_e32 v6, v6
	v_cvt_f32_i32_e32 v7, v7
	v_cvt_f32_i32_e32 v8, v8
	v_cvt_f32_i32_e32 v9, v9
	v_cvt_f32_i32_e32 v2, v2
	v_cvt_f32_i32_e32 v3, v3
	v_cvt_f32_i32_e32 v4, v4
	s_and_b64 vcc, exec, s[4:5]
	v_mov_b32_e32 v153, v192
	v_mul_f32_e32 v167, v160, v153
	v_mul_f32_e32 v170, v161, v153
	v_mul_f32_e32 v173, v156, v153
	v_mul_f32_e32 v174, v157, v153
	v_mul_f32_e32 v175, v158, v153
	v_mul_f32_e32 v176, v159, v153
	v_mul_f32_e32 v177, v126, v153
	v_mul_f32_e32 v153, v127, v153
	v_mul_f32_e32 v118, v167, v118
	v_mul_f32_e32 v119, v170, v119
	v_mul_f32_e32 v120, v173, v120
	v_mul_f32_e32 v121, v174, v121
	v_mul_f32_e32 v167, v175, v168
	v_mul_f32_e32 v168, v176, v169
	v_mul_f32_e32 v169, v177, v171
	v_mul_f32_e32 v153, v153, v172
	v_exp_f32_e64 v170, -v118
	v_exp_f32_e64 v171, -v119
	v_exp_f32_e64 v172, -v120
	v_exp_f32_e64 v173, -v121
	v_exp_f32_e64 v174, -v167
	v_exp_f32_e64 v175, -v168
	v_exp_f32_e64 v176, -v169
	v_exp_f32_e64 v177, -v153
	v_add_f32_e32 v170, 1.0, v170
	v_add_f32_e32 v171, 1.0, v171
	v_add_f32_e32 v172, 1.0, v172
	v_add_f32_e32 v173, 1.0, v173
	v_add_f32_e32 v174, 1.0, v174
	v_add_f32_e32 v175, 1.0, v175
	v_add_f32_e32 v176, 1.0, v176
	v_add_f32_e32 v177, 1.0, v177
	v_rcp_f32_e32 v170, v170
	v_rcp_f32_e32 v171, v171
	v_rcp_f32_e32 v172, v172
	v_rcp_f32_e32 v173, v173
	v_rcp_f32_e32 v174, v174
	v_rcp_f32_e32 v175, v175
	v_rcp_f32_e32 v176, v176
	v_rcp_f32_e32 v177, v177
	v_cvt_pk_bf16_f32 v118, v170, v171
	v_cvt_pk_bf16_f32 v119, v172, v173
	v_cvt_pk_bf16_f32 v120, v174, v175
	v_cvt_pk_bf16_f32 v121, v176, v177
	global_store_dwordx4 v[114:115], v[118:121], off
	s_nop 1
	v_cvt_f32_i32_e32 v153, v107
	v_cvt_f32_i32_e32 v121, v106
	v_cvt_f32_i32_e32 v167, v108
	v_cvt_f32_i32_e32 v168, v109
	v_or_b32_e32 v118, 48, v152
	v_ashrrev_i32_e32 v119, 31, v118
	v_mad_i64_i32 v[106:107], s[0:1], v166, s65, v[154:155]
	v_lshl_add_u64 v[108:109], v[118:119], 2, s[26:27]
	v_lshl_add_u64 v[106:107], v[106:107], 0, v[128:129]
	v_mov_b32_e32 v120, v194
	v_mul_f32_e32 v119, v160, v120
	v_mul_f32_e32 v166, v161, v120
	v_mul_f32_e32 v169, v156, v120
	v_mul_f32_e32 v170, v157, v120
	v_mul_f32_e32 v171, v158, v120
	v_mul_f32_e32 v172, v159, v120
	v_mul_f32_e32 v173, v126, v120
	v_mul_f32_e32 v120, v127, v120
	v_mul_f32_e32 v110, v119, v110
	v_mul_f32_e32 v111, v166, v111
	v_mul_f32_e32 v112, v169, v112
	v_mul_f32_e32 v113, v170, v113
	v_mul_f32_e32 v119, v171, v121
	v_mul_f32_e32 v121, v172, v153
	v_mul_f32_e32 v153, v173, v167
	v_mul_f32_e32 v120, v120, v168
	v_exp_f32_e64 v166, -v110
	v_exp_f32_e64 v167, -v111
	v_exp_f32_e64 v168, -v112
	v_exp_f32_e64 v169, -v113
	v_exp_f32_e64 v170, -v119
	v_exp_f32_e64 v171, -v121
	v_exp_f32_e64 v172, -v153
	v_exp_f32_e64 v173, -v120
	v_add_f32_e32 v166, 1.0, v166
	v_add_f32_e32 v167, 1.0, v167
	v_add_f32_e32 v168, 1.0, v168
	v_add_f32_e32 v169, 1.0, v169
	v_add_f32_e32 v170, 1.0, v170
	v_add_f32_e32 v171, 1.0, v171
	v_add_f32_e32 v172, 1.0, v172
	v_add_f32_e32 v173, 1.0, v173
	v_rcp_f32_e32 v166, v166
	v_rcp_f32_e32 v167, v167
	v_rcp_f32_e32 v168, v168
	v_rcp_f32_e32 v169, v169
	v_rcp_f32_e32 v170, v170
	v_rcp_f32_e32 v171, v171
	v_rcp_f32_e32 v172, v172
	v_rcp_f32_e32 v173, v173
	v_cvt_pk_bf16_f32 v110, v166, v167
	v_cvt_pk_bf16_f32 v111, v168, v169
	v_cvt_pk_bf16_f32 v112, v170, v171
	v_cvt_pk_bf16_f32 v113, v172, v173
	global_store_dwordx4 v[106:107], v[110:113], off
	s_nop 1
	v_mov_b32_e32 v110, v196
	v_mul_f32_e32 v119, v156, v110
	v_cvt_f32_i32_e32 v111, v98
	v_cvt_f32_i32_e32 v112, v99
	v_mad_i64_i32 v[98:99], s[0:1], v118, s65, v[154:155]
	v_mul_f32_e32 v113, v160, v110
	v_mul_f32_e32 v118, v161, v110
	v_mul_f32_e32 v120, v157, v110
	v_mul_f32_e32 v121, v158, v110
	v_mul_f32_e32 v153, v159, v110
	v_mul_f32_e32 v166, v126, v110
	v_mul_f32_e32 v110, v127, v110
	v_mul_f32_e32 v102, v113, v102
	v_mul_f32_e32 v103, v118, v103
	v_mul_f32_e32 v104, v119, v104
	v_mul_f32_e32 v105, v120, v105
	v_mul_f32_e32 v111, v121, v111
	v_mul_f32_e32 v112, v153, v112
	v_mul_f32_e32 v100, v166, v100
	v_mul_f32_e32 v101, v110, v101
	v_exp_f32_e64 v110, -v102
	v_exp_f32_e64 v113, -v103
	v_exp_f32_e64 v118, -v104
	v_exp_f32_e64 v119, -v105
	v_exp_f32_e64 v120, -v111
	v_exp_f32_e64 v121, -v112
	v_exp_f32_e64 v153, -v100
	v_exp_f32_e64 v166, -v101
	v_add_f32_e32 v110, 1.0, v110
	v_add_f32_e32 v113, 1.0, v113
	v_add_f32_e32 v118, 1.0, v118
	v_add_f32_e32 v119, 1.0, v119
	v_add_f32_e32 v120, 1.0, v120
	v_add_f32_e32 v121, 1.0, v121
	v_add_f32_e32 v153, 1.0, v153
	v_add_f32_e32 v166, 1.0, v166
	v_rcp_f32_e32 v110, v110
	v_rcp_f32_e32 v113, v113
	v_rcp_f32_e32 v118, v118
	v_rcp_f32_e32 v119, v119
	v_rcp_f32_e32 v120, v120
	v_rcp_f32_e32 v121, v121
	v_rcp_f32_e32 v153, v153
	v_rcp_f32_e32 v166, v166
	v_lshl_add_u64 v[98:99], v[98:99], 0, v[128:129]
	v_cvt_pk_bf16_f32 v100, v110, v113
	v_cvt_pk_bf16_f32 v101, v118, v119
	v_cvt_pk_bf16_f32 v102, v120, v121
	v_cvt_pk_bf16_f32 v103, v153, v166
	global_store_dwordx4 v[98:99], v[100:103], off
	s_nop 1
	v_mov_b32_e32 v100, v198
	v_mul_f32_e32 v104, v161, v100
	v_cvt_f32_i32_e32 v101, v90
	v_cvt_f32_i32_e32 v102, v91
	v_mul_f32_e32 v103, v160, v100
	v_mul_f32_e32 v105, v156, v100
	v_mul_f32_e32 v110, v157, v100
	v_mul_f32_e32 v111, v158, v100
	v_mul_f32_e32 v112, v159, v100
	v_mul_f32_e32 v113, v126, v100
	v_mul_f32_e32 v100, v127, v100
	v_mul_f32_e32 v94, v103, v94
	v_mul_f32_e32 v95, v104, v95
	v_mul_f32_e32 v96, v105, v96
	v_mul_f32_e32 v97, v110, v97
	v_mul_f32_e32 v101, v111, v101
	v_mul_f32_e32 v102, v112, v102
	v_mul_f32_e32 v92, v113, v92
	v_mul_f32_e32 v93, v100, v93
	v_exp_f32_e64 v100, -v94
	v_exp_f32_e64 v103, -v95
	v_exp_f32_e64 v104, -v96
	v_exp_f32_e64 v105, -v97
	v_exp_f32_e64 v110, -v101
	v_exp_f32_e64 v111, -v102
	v_exp_f32_e64 v112, -v92
	v_exp_f32_e64 v113, -v93
	v_add_f32_e32 v100, 1.0, v100
	v_add_f32_e32 v103, 1.0, v103
	v_add_f32_e32 v104, 1.0, v104
	v_add_f32_e32 v105, 1.0, v105
	v_add_f32_e32 v110, 1.0, v110
	v_add_f32_e32 v111, 1.0, v111
	v_add_f32_e32 v112, 1.0, v112
	v_add_f32_e32 v113, 1.0, v113
	v_rcp_f32_e32 v100, v100
	v_rcp_f32_e32 v103, v103
	v_rcp_f32_e32 v104, v104
	v_rcp_f32_e32 v105, v105
	v_rcp_f32_e32 v110, v110
	v_rcp_f32_e32 v111, v111
	v_rcp_f32_e32 v112, v112
	v_rcp_f32_e32 v113, v113
	v_add_u32_e32 v90, 0x80, v152
	v_mad_i64_i32 v[90:91], s[0:1], v90, s65, v[154:155]
	v_lshl_add_u64 v[90:91], v[90:91], 0, v[128:129]
	v_cvt_pk_bf16_f32 v92, v100, v103
	v_cvt_pk_bf16_f32 v93, v104, v105
	v_cvt_pk_bf16_f32 v94, v110, v111
	v_cvt_pk_bf16_f32 v95, v112, v113
	global_store_dwordx4 v[90:91], v[92:95], off
	s_nop 1
	v_mov_b32_e32 v92, v200
	v_mul_f32_e32 v96, v161, v92
	v_cvt_f32_i32_e32 v93, v82
	v_cvt_f32_i32_e32 v94, v83
	v_mul_f32_e32 v95, v160, v92
	v_mul_f32_e32 v97, v156, v92
	v_mul_f32_e32 v100, v157, v92
	v_mul_f32_e32 v101, v158, v92
	v_mul_f32_e32 v102, v159, v92
	v_mul_f32_e32 v103, v126, v92
	v_mul_f32_e32 v92, v127, v92
	v_mul_f32_e32 v86, v95, v86
	v_mul_f32_e32 v87, v96, v87
	v_mul_f32_e32 v88, v97, v88
	v_mul_f32_e32 v89, v100, v89
	v_mul_f32_e32 v93, v101, v93
	v_mul_f32_e32 v94, v102, v94
	v_mul_f32_e32 v84, v103, v84
	v_mul_f32_e32 v85, v92, v85
	v_exp_f32_e64 v92, -v86
	v_exp_f32_e64 v95, -v87
	v_exp_f32_e64 v96, -v88
	v_exp_f32_e64 v97, -v89
	v_exp_f32_e64 v100, -v93
	v_exp_f32_e64 v101, -v94
	v_exp_f32_e64 v102, -v84
	v_exp_f32_e64 v103, -v85
	v_add_f32_e32 v92, 1.0, v92
	v_add_f32_e32 v95, 1.0, v95
	v_add_f32_e32 v96, 1.0, v96
	v_add_f32_e32 v97, 1.0, v97
	v_add_f32_e32 v100, 1.0, v100
	v_add_f32_e32 v101, 1.0, v101
	v_add_f32_e32 v102, 1.0, v102
	v_add_f32_e32 v103, 1.0, v103
	v_rcp_f32_e32 v92, v92
	v_rcp_f32_e32 v95, v95
	v_rcp_f32_e32 v96, v96
	v_rcp_f32_e32 v97, v97
	v_rcp_f32_e32 v100, v100
	v_rcp_f32_e32 v101, v101
	v_rcp_f32_e32 v102, v102
	v_rcp_f32_e32 v103, v103
	v_add_u32_e32 v82, 0x90, v152
	v_mad_i64_i32 v[82:83], s[0:1], v82, s65, v[154:155]
	v_lshl_add_u64 v[82:83], v[82:83], 0, v[128:129]
	v_cvt_pk_bf16_f32 v84, v92, v95
	v_cvt_pk_bf16_f32 v85, v96, v97
	v_cvt_pk_bf16_f32 v86, v100, v101
	v_cvt_pk_bf16_f32 v87, v102, v103
	global_store_dwordx4 v[82:83], v[84:87], off
	s_nop 1
	v_mov_b32_e32 v84, v202
	v_mul_f32_e32 v88, v161, v84
	v_cvt_f32_i32_e32 v85, v74
	v_cvt_f32_i32_e32 v86, v75
	v_mul_f32_e32 v87, v160, v84
	v_mul_f32_e32 v89, v156, v84
	v_mul_f32_e32 v92, v157, v84
	v_mul_f32_e32 v93, v158, v84
	v_mul_f32_e32 v94, v159, v84
	v_mul_f32_e32 v95, v126, v84
	v_mul_f32_e32 v84, v127, v84
	v_mul_f32_e32 v78, v87, v78
	v_mul_f32_e32 v79, v88, v79
	v_mul_f32_e32 v80, v89, v80
	v_mul_f32_e32 v81, v92, v81
	v_mul_f32_e32 v85, v93, v85
	v_mul_f32_e32 v86, v94, v86
	v_mul_f32_e32 v76, v95, v76
	v_mul_f32_e32 v77, v84, v77
	v_exp_f32_e64 v84, -v78
	v_exp_f32_e64 v87, -v79
	v_exp_f32_e64 v88, -v80
	v_exp_f32_e64 v89, -v81
	v_exp_f32_e64 v92, -v85
	v_exp_f32_e64 v93, -v86
	v_exp_f32_e64 v94, -v76
	v_exp_f32_e64 v95, -v77
	v_add_f32_e32 v84, 1.0, v84
	v_add_f32_e32 v87, 1.0, v87
	v_add_f32_e32 v88, 1.0, v88
	v_add_f32_e32 v89, 1.0, v89
	v_add_f32_e32 v92, 1.0, v92
	v_add_f32_e32 v93, 1.0, v93
	v_add_f32_e32 v94, 1.0, v94
	v_add_f32_e32 v95, 1.0, v95
	v_rcp_f32_e32 v84, v84
	v_rcp_f32_e32 v87, v87
	v_rcp_f32_e32 v88, v88
	v_rcp_f32_e32 v89, v89
	v_rcp_f32_e32 v92, v92
	v_rcp_f32_e32 v93, v93
	v_rcp_f32_e32 v94, v94
	v_rcp_f32_e32 v95, v95
	v_add_u32_e32 v74, 0xa0, v152
	v_mad_i64_i32 v[74:75], s[0:1], v74, s65, v[154:155]
	v_lshl_add_u64 v[74:75], v[74:75], 0, v[128:129]
	v_cvt_pk_bf16_f32 v76, v84, v87
	v_cvt_pk_bf16_f32 v77, v88, v89
	v_cvt_pk_bf16_f32 v78, v92, v93
	v_cvt_pk_bf16_f32 v79, v94, v95
	global_store_dwordx4 v[74:75], v[76:79], off
	s_nop 1
	v_cvt_f32_i32_e32 v88, v61
	v_cvt_f32_i32_e32 v77, v66
	v_cvt_f32_i32_e32 v78, v67
	v_add_u32_e32 v66, 0xb0, v152
	v_mad_i64_i32 v[66:67], s[0:1], v66, s65, v[154:155]
	v_lshl_add_u64 v[66:67], v[66:67], 0, v[128:129]
	s_mov_b64 s[0:1], -1
	v_mov_b32_e32 v76, v204
	v_mul_f32_e32 v79, v160, v76
	v_mul_f32_e32 v80, v161, v76
	v_mul_f32_e32 v81, v156, v76
	v_mul_f32_e32 v84, v157, v76
	v_mul_f32_e32 v85, v158, v76
	v_mul_f32_e32 v86, v159, v76
	v_mul_f32_e32 v87, v126, v76
	v_mul_f32_e32 v76, v127, v76
	v_mul_f32_e32 v70, v79, v70
	v_mul_f32_e32 v71, v80, v71
	v_mul_f32_e32 v72, v81, v72
	v_mul_f32_e32 v73, v84, v73
	v_mul_f32_e32 v77, v85, v77
	v_mul_f32_e32 v78, v86, v78
	v_mul_f32_e32 v68, v87, v68
	v_mul_f32_e32 v69, v76, v69
	v_exp_f32_e64 v76, -v70
	v_exp_f32_e64 v79, -v71
	v_exp_f32_e64 v80, -v72
	v_exp_f32_e64 v81, -v73
	v_exp_f32_e64 v84, -v77
	v_exp_f32_e64 v85, -v78
	v_exp_f32_e64 v86, -v68
	v_exp_f32_e64 v87, -v69
	v_add_f32_e32 v76, 1.0, v76
	v_add_f32_e32 v79, 1.0, v79
	v_add_f32_e32 v80, 1.0, v80
	v_add_f32_e32 v81, 1.0, v81
	v_add_f32_e32 v84, 1.0, v84
	v_add_f32_e32 v85, 1.0, v85
	v_add_f32_e32 v86, 1.0, v86
	v_add_f32_e32 v87, 1.0, v87
	v_rcp_f32_e32 v76, v76
	v_rcp_f32_e32 v79, v79
	v_rcp_f32_e32 v80, v80
	v_rcp_f32_e32 v81, v81
	v_rcp_f32_e32 v84, v84
	v_rcp_f32_e32 v85, v85
	v_rcp_f32_e32 v86, v86
	v_rcp_f32_e32 v87, v87
	v_cvt_pk_bf16_f32 v68, v76, v79
	v_cvt_pk_bf16_f32 v69, v80, v81
	v_cvt_pk_bf16_f32 v70, v84, v85
	v_cvt_pk_bf16_f32 v71, v86, v87
	global_store_dwordx4 v[66:67], v[68:71], off
	s_nop 1
	s_nop 1
	v_cvt_f32_i32_e32 v73, v62
	v_cvt_f32_i32_e32 v80, v63
	v_cvt_f32_i32_e32 v81, v64
	v_cvt_f32_i32_e32 v84, v65
	v_cvt_f32_i32_e32 v85, v58
	v_cvt_f32_i32_e32 v86, v59
	v_cvt_f32_i32_e32 v87, v60
	v_pk_mul_f32 v[60:61], v[208:209], s[98:99] op_sel_hi:[1,0]
	v_pk_mul_f32 v[64:65], v[206:207], s[98:99] op_sel_hi:[1,0]
	v_pk_mul_f32 v[58:59], v[212:213], s[98:99] op_sel_hi:[1,0]
	v_pk_mul_f32 v[62:63], v[210:211], s[98:99] op_sel_hi:[1,0]
	v_mov_b32_e32 v72, v190
	v_mul_f32_e32 v68, v64, v72
	v_mul_f32_e32 v69, v65, v72
	v_mul_f32_e32 v70, v60, v72
	v_mul_f32_e32 v71, v61, v72
	v_mul_f32_e32 v76, v72, v62
	v_mul_f32_e32 v77, v72, v63
	v_mul_f32_e32 v78, v72, v58
	v_mul_f32_e32 v72, v72, v59
	v_mul_f32_e32 v68, v68, v73
	v_mul_f32_e32 v69, v69, v80
	v_mul_f32_e32 v70, v70, v81
	v_mul_f32_e32 v71, v71, v84
	v_mul_f32_e32 v73, v76, v85
	v_mul_f32_e32 v76, v77, v86
	v_mul_f32_e32 v77, v78, v87
	v_mul_f32_e32 v72, v72, v88
	v_exp_f32_e64 v78, -v68
	v_exp_f32_e64 v79, -v69
	v_exp_f32_e64 v80, -v70
	v_exp_f32_e64 v81, -v71
	v_exp_f32_e64 v84, -v73
	v_exp_f32_e64 v85, -v76
	v_exp_f32_e64 v86, -v77
	v_exp_f32_e64 v87, -v72
	v_add_f32_e32 v78, 1.0, v78
	v_add_f32_e32 v79, 1.0, v79
	v_add_f32_e32 v80, 1.0, v80
	v_add_f32_e32 v81, 1.0, v81
	v_add_f32_e32 v84, 1.0, v84
	v_add_f32_e32 v85, 1.0, v85
	v_add_f32_e32 v86, 1.0, v86
	v_add_f32_e32 v87, 1.0, v87
	v_rcp_f32_e32 v78, v78
	v_rcp_f32_e32 v79, v79
	v_rcp_f32_e32 v80, v80
	v_rcp_f32_e32 v81, v81
	v_rcp_f32_e32 v84, v84
	v_rcp_f32_e32 v85, v85
	v_rcp_f32_e32 v86, v86
	v_rcp_f32_e32 v87, v87
	v_cvt_pk_bf16_f32 v68, v78, v79
	v_cvt_pk_bf16_f32 v69, v80, v81
	v_cvt_pk_bf16_f32 v70, v84, v85
	v_cvt_pk_bf16_f32 v71, v86, v87
	global_store_dwordx4 v[122:123], v[68:71], off offset:256
	s_nop 1
	v_mov_b32_e32 v68, v192
	v_mul_f32_e32 v72, v61, v68
	v_mul_f32_e32 v69, v64, v68
	v_mul_f32_e32 v70, v65, v68
	v_mul_f32_e32 v71, v60, v68
	v_mul_f32_e32 v73, v62, v68
	v_mul_f32_e32 v76, v63, v68
	v_mul_f32_e32 v77, v58, v68
	v_mul_f32_e32 v68, v59, v68
	v_mul_f32_e32 v53, v68, v53
	v_mul_f32_e32 v54, v69, v54
	v_mul_f32_e32 v55, v70, v55
	v_mul_f32_e32 v56, v71, v56
	v_mul_f32_e32 v57, v72, v57
	v_mul_f32_e32 v50, v73, v50
	v_mul_f32_e32 v51, v76, v51
	v_mul_f32_e32 v52, v77, v52
	v_exp_f32_e64 v77, -v53
	v_exp_f32_e64 v68, -v54
	v_exp_f32_e64 v69, -v55
	v_exp_f32_e64 v70, -v56
	v_exp_f32_e64 v71, -v57
	v_exp_f32_e64 v72, -v50
	v_exp_f32_e64 v73, -v51
	v_exp_f32_e64 v76, -v52
	v_add_f32_e32 v77, 1.0, v77
	v_add_f32_e32 v68, 1.0, v68
	v_add_f32_e32 v69, 1.0, v69
	v_add_f32_e32 v70, 1.0, v70
	v_add_f32_e32 v71, 1.0, v71
	v_add_f32_e32 v72, 1.0, v72
	v_add_f32_e32 v73, 1.0, v73
	v_add_f32_e32 v76, 1.0, v76
	v_rcp_f32_e32 v77, v77
	v_rcp_f32_e32 v68, v68
	v_rcp_f32_e32 v69, v69
	v_rcp_f32_e32 v70, v70
	v_rcp_f32_e32 v71, v71
	v_rcp_f32_e32 v72, v72
	v_rcp_f32_e32 v73, v73
	v_rcp_f32_e32 v76, v76
	v_cvt_pk_bf16_f32 v50, v68, v69
	v_cvt_pk_bf16_f32 v51, v70, v71
	v_cvt_pk_bf16_f32 v52, v72, v73
	v_cvt_pk_bf16_f32 v53, v76, v77
	global_store_dwordx4 v[114:115], v[50:53], off offset:256
	s_nop 1
	v_mov_b32_e32 v50, v194
	v_mul_f32_e32 v54, v61, v50
	v_mul_f32_e32 v51, v64, v50
	v_mul_f32_e32 v52, v65, v50
	v_mul_f32_e32 v53, v60, v50
	v_mul_f32_e32 v55, v62, v50
	v_mul_f32_e32 v56, v63, v50
	v_mul_f32_e32 v57, v58, v50
	v_mul_f32_e32 v50, v59, v50
	v_mul_f32_e32 v45, v50, v45
	v_mul_f32_e32 v46, v51, v46
	v_mul_f32_e32 v47, v52, v47
	v_mul_f32_e32 v48, v53, v48
	v_mul_f32_e32 v49, v54, v49
	v_mul_f32_e32 v42, v55, v42
	v_mul_f32_e32 v43, v56, v43
	v_mul_f32_e32 v44, v57, v44
	v_exp_f32_e64 v57, -v45
	v_exp_f32_e64 v50, -v46
	v_exp_f32_e64 v51, -v47
	v_exp_f32_e64 v52, -v48
	v_exp_f32_e64 v53, -v49
	v_exp_f32_e64 v54, -v42
	v_exp_f32_e64 v55, -v43
	v_exp_f32_e64 v56, -v44
	v_add_f32_e32 v57, 1.0, v57
	v_add_f32_e32 v50, 1.0, v50
	v_add_f32_e32 v51, 1.0, v51
	v_add_f32_e32 v52, 1.0, v52
	v_add_f32_e32 v53, 1.0, v53
	v_add_f32_e32 v54, 1.0, v54
	v_add_f32_e32 v55, 1.0, v55
	v_add_f32_e32 v56, 1.0, v56
	v_rcp_f32_e32 v57, v57
	v_rcp_f32_e32 v50, v50
	v_rcp_f32_e32 v51, v51
	v_rcp_f32_e32 v52, v52
	v_rcp_f32_e32 v53, v53
	v_rcp_f32_e32 v54, v54
	v_rcp_f32_e32 v55, v55
	v_rcp_f32_e32 v56, v56
	v_cvt_pk_bf16_f32 v42, v50, v51
	v_cvt_pk_bf16_f32 v43, v52, v53
	v_cvt_pk_bf16_f32 v44, v54, v55
	v_cvt_pk_bf16_f32 v45, v56, v57
	global_store_dwordx4 v[106:107], v[42:45], off offset:256
	s_nop 1
	v_mov_b32_e32 v42, v196
	v_mul_f32_e32 v46, v61, v42
	v_mul_f32_e32 v43, v64, v42
	v_mul_f32_e32 v44, v65, v42
	v_mul_f32_e32 v45, v60, v42
	v_mul_f32_e32 v47, v62, v42
	v_mul_f32_e32 v48, v63, v42
	v_mul_f32_e32 v49, v58, v42
	v_mul_f32_e32 v42, v59, v42
	v_mul_f32_e32 v37, v42, v37
	v_mul_f32_e32 v38, v43, v38
	v_mul_f32_e32 v39, v44, v39
	v_mul_f32_e32 v40, v45, v40
	v_mul_f32_e32 v41, v46, v41
	v_mul_f32_e32 v34, v47, v34
	v_mul_f32_e32 v35, v48, v35
	v_mul_f32_e32 v36, v49, v36
	v_exp_f32_e64 v49, -v37
	v_exp_f32_e64 v42, -v38
	v_exp_f32_e64 v43, -v39
	v_exp_f32_e64 v44, -v40
	v_exp_f32_e64 v45, -v41
	v_exp_f32_e64 v46, -v34
	v_exp_f32_e64 v47, -v35
	v_exp_f32_e64 v48, -v36
	v_add_f32_e32 v49, 1.0, v49
	v_add_f32_e32 v42, 1.0, v42
	v_add_f32_e32 v43, 1.0, v43
	v_add_f32_e32 v44, 1.0, v44
	v_add_f32_e32 v45, 1.0, v45
	v_add_f32_e32 v46, 1.0, v46
	v_add_f32_e32 v47, 1.0, v47
	v_add_f32_e32 v48, 1.0, v48
	v_rcp_f32_e32 v49, v49
	v_rcp_f32_e32 v42, v42
	v_rcp_f32_e32 v43, v43
	v_rcp_f32_e32 v44, v44
	v_rcp_f32_e32 v45, v45
	v_rcp_f32_e32 v46, v46
	v_rcp_f32_e32 v47, v47
	v_rcp_f32_e32 v48, v48
	v_cvt_pk_bf16_f32 v34, v42, v43
	v_cvt_pk_bf16_f32 v35, v44, v45
	v_cvt_pk_bf16_f32 v36, v46, v47
	v_cvt_pk_bf16_f32 v37, v48, v49
	global_store_dwordx4 v[98:99], v[34:37], off offset:256
	s_nop 1
	v_mov_b32_e32 v34, v198
	v_mul_f32_e32 v38, v61, v34
	v_mul_f32_e32 v35, v64, v34
	v_mul_f32_e32 v36, v65, v34
	v_mul_f32_e32 v37, v60, v34
	v_mul_f32_e32 v39, v62, v34
	v_mul_f32_e32 v40, v63, v34
	v_mul_f32_e32 v41, v58, v34
	v_mul_f32_e32 v34, v59, v34
	v_mul_f32_e32 v29, v34, v29
	v_mul_f32_e32 v30, v35, v30
	v_mul_f32_e32 v31, v36, v31
	v_mul_f32_e32 v32, v37, v32
	v_mul_f32_e32 v33, v38, v33
	v_mul_f32_e32 v26, v39, v26
	v_mul_f32_e32 v27, v40, v27
	v_mul_f32_e32 v28, v41, v28
	v_exp_f32_e64 v41, -v29
	v_exp_f32_e64 v34, -v30
	v_exp_f32_e64 v35, -v31
	v_exp_f32_e64 v36, -v32
	v_exp_f32_e64 v37, -v33
	v_exp_f32_e64 v38, -v26
	v_exp_f32_e64 v39, -v27
	v_exp_f32_e64 v40, -v28
	v_add_f32_e32 v41, 1.0, v41
	v_add_f32_e32 v34, 1.0, v34
	v_add_f32_e32 v35, 1.0, v35
	v_add_f32_e32 v36, 1.0, v36
	v_add_f32_e32 v37, 1.0, v37
	v_add_f32_e32 v38, 1.0, v38
	v_add_f32_e32 v39, 1.0, v39
	v_add_f32_e32 v40, 1.0, v40
	v_rcp_f32_e32 v41, v41
	v_rcp_f32_e32 v34, v34
	v_rcp_f32_e32 v35, v35
	v_rcp_f32_e32 v36, v36
	v_rcp_f32_e32 v37, v37
	v_rcp_f32_e32 v38, v38
	v_rcp_f32_e32 v39, v39
	v_rcp_f32_e32 v40, v40
	v_cvt_pk_bf16_f32 v26, v34, v35
	v_cvt_pk_bf16_f32 v27, v36, v37
	v_cvt_pk_bf16_f32 v28, v38, v39
	v_cvt_pk_bf16_f32 v29, v40, v41
	global_store_dwordx4 v[90:91], v[26:29], off offset:256
	s_nop 1
	v_mov_b32_e32 v26, v200
	v_mul_f32_e32 v30, v61, v26
	v_mul_f32_e32 v27, v64, v26
	v_mul_f32_e32 v28, v65, v26
	v_mul_f32_e32 v29, v60, v26
	v_mul_f32_e32 v31, v62, v26
	v_mul_f32_e32 v32, v63, v26
	v_mul_f32_e32 v33, v58, v26
	v_mul_f32_e32 v26, v59, v26
	v_mul_f32_e32 v21, v26, v21
	v_mul_f32_e32 v22, v27, v22
	v_mul_f32_e32 v23, v28, v23
	v_mul_f32_e32 v24, v29, v24
	v_mul_f32_e32 v25, v30, v25
	v_mul_f32_e32 v18, v31, v18
	v_mul_f32_e32 v19, v32, v19
	v_mul_f32_e32 v20, v33, v20
	v_exp_f32_e64 v33, -v21
	v_exp_f32_e64 v26, -v22
	v_exp_f32_e64 v27, -v23
	v_exp_f32_e64 v28, -v24
	v_exp_f32_e64 v29, -v25
	v_exp_f32_e64 v30, -v18
	v_exp_f32_e64 v31, -v19
	v_exp_f32_e64 v32, -v20
	v_add_f32_e32 v33, 1.0, v33
	v_add_f32_e32 v26, 1.0, v26
	v_add_f32_e32 v27, 1.0, v27
	v_add_f32_e32 v28, 1.0, v28
	v_add_f32_e32 v29, 1.0, v29
	v_add_f32_e32 v30, 1.0, v30
	v_add_f32_e32 v31, 1.0, v31
	v_add_f32_e32 v32, 1.0, v32
	v_rcp_f32_e32 v33, v33
	v_rcp_f32_e32 v26, v26
	v_rcp_f32_e32 v27, v27
	v_rcp_f32_e32 v28, v28
	v_rcp_f32_e32 v29, v29
	v_rcp_f32_e32 v30, v30
	v_rcp_f32_e32 v31, v31
	v_rcp_f32_e32 v32, v32
	v_cvt_pk_bf16_f32 v18, v26, v27
	v_cvt_pk_bf16_f32 v19, v28, v29
	v_cvt_pk_bf16_f32 v20, v30, v31
	v_cvt_pk_bf16_f32 v21, v32, v33
	global_store_dwordx4 v[82:83], v[18:21], off offset:256
	s_nop 1
	v_mov_b32_e32 v18, v202
	v_mul_f32_e32 v22, v61, v18
	v_mul_f32_e32 v19, v64, v18
	v_mul_f32_e32 v20, v65, v18
	v_mul_f32_e32 v21, v60, v18
	v_mul_f32_e32 v23, v62, v18
	v_mul_f32_e32 v24, v63, v18
	v_mul_f32_e32 v25, v58, v18
	v_mul_f32_e32 v18, v59, v18
	v_mul_f32_e32 v13, v18, v13
	v_mul_f32_e32 v14, v19, v14
	v_mul_f32_e32 v15, v20, v15
	v_mul_f32_e32 v16, v21, v16
	v_mul_f32_e32 v17, v22, v17
	v_mul_f32_e32 v10, v23, v10
	v_mul_f32_e32 v11, v24, v11
	v_mul_f32_e32 v12, v25, v12
	v_exp_f32_e64 v25, -v13
	v_exp_f32_e64 v18, -v14
	v_exp_f32_e64 v19, -v15
	v_exp_f32_e64 v20, -v16
	v_exp_f32_e64 v21, -v17
	v_exp_f32_e64 v22, -v10
	v_exp_f32_e64 v23, -v11
	v_exp_f32_e64 v24, -v12
	v_add_f32_e32 v25, 1.0, v25
	v_add_f32_e32 v18, 1.0, v18
	v_add_f32_e32 v19, 1.0, v19
	v_add_f32_e32 v20, 1.0, v20
	v_add_f32_e32 v21, 1.0, v21
	v_add_f32_e32 v22, 1.0, v22
	v_add_f32_e32 v23, 1.0, v23
	v_add_f32_e32 v24, 1.0, v24
	v_rcp_f32_e32 v25, v25
	v_rcp_f32_e32 v18, v18
	v_rcp_f32_e32 v19, v19
	v_rcp_f32_e32 v20, v20
	v_rcp_f32_e32 v21, v21
	v_rcp_f32_e32 v22, v22
	v_rcp_f32_e32 v23, v23
	v_rcp_f32_e32 v24, v24
	v_cvt_pk_bf16_f32 v10, v18, v19
	v_cvt_pk_bf16_f32 v11, v20, v21
	v_cvt_pk_bf16_f32 v12, v22, v23
	v_cvt_pk_bf16_f32 v13, v24, v25
	global_store_dwordx4 v[74:75], v[10:13], off offset:256
	s_nop 1
	v_mov_b32_e32 v10, v204
	v_mul_f32_e32 v14, v61, v10
	v_mul_f32_e32 v11, v64, v10
	v_mul_f32_e32 v12, v65, v10
	v_mul_f32_e32 v13, v60, v10
	v_mul_f32_e32 v15, v62, v10
	v_mul_f32_e32 v16, v63, v10
	v_mul_f32_e32 v17, v58, v10
	v_mul_f32_e32 v10, v59, v10
	v_mul_f32_e32 v5, v10, v5
	v_mul_f32_e32 v6, v11, v6
	v_mul_f32_e32 v7, v12, v7
	v_mul_f32_e32 v8, v13, v8
	v_mul_f32_e32 v9, v14, v9
	v_mul_f32_e32 v2, v15, v2
	v_mul_f32_e32 v3, v16, v3
	v_mul_f32_e32 v4, v17, v4
	v_exp_f32_e64 v17, -v5
	v_exp_f32_e64 v10, -v6
	v_exp_f32_e64 v11, -v7
	v_exp_f32_e64 v12, -v8
	v_exp_f32_e64 v13, -v9
	v_exp_f32_e64 v14, -v2
	v_exp_f32_e64 v15, -v3
	v_exp_f32_e64 v16, -v4
	v_add_f32_e32 v17, 1.0, v17
	v_add_f32_e32 v10, 1.0, v10
	v_add_f32_e32 v11, 1.0, v11
	v_add_f32_e32 v12, 1.0, v12
	v_add_f32_e32 v13, 1.0, v13
	v_add_f32_e32 v14, 1.0, v14
	v_add_f32_e32 v15, 1.0, v15
	v_add_f32_e32 v16, 1.0, v16
	v_rcp_f32_e32 v17, v17
	v_rcp_f32_e32 v10, v10
	v_rcp_f32_e32 v11, v11
	v_rcp_f32_e32 v12, v12
	v_rcp_f32_e32 v13, v13
	v_rcp_f32_e32 v14, v14
	v_rcp_f32_e32 v15, v15
	v_rcp_f32_e32 v16, v16
	v_cvt_pk_bf16_f32 v2, v10, v11
	v_cvt_pk_bf16_f32 v3, v12, v13
	v_cvt_pk_bf16_f32 v4, v14, v15
	v_cvt_pk_bf16_f32 v5, v16, v17
	global_store_dwordx4 v[66:67], v[2:5], off offset:256
	s_cbranch_vccnz .LBB0_600
	s_andn2_b64 vcc, exec, s[10:11]
	s_cbranch_vccnz .LBB0_599
	s_barrier
	s_branch .LBB0_599

.LBB0_1435:
	v_lshl_or_b32 v170, s77, 7, v156
	v_ashrrev_i32_e32 v171, 31, v170
	v_lshlrev_b64 v[148:149], 2, v[170:171]
	v_lshl_add_u64 v[150:151], s[20:21], 0, v[148:149]
	v_lshl_add_u64 v[148:149], s[24:25], 0, v[148:149]
	global_load_dwordx4 v[152:155], v[150:151], off
	global_load_dwordx4 v[158:161], v[148:149], off
	global_load_dwordx4 v[162:165], v[150:151], off offset:16
	global_load_dwordx4 v[166:169], v[148:149], off offset:16
	v_lshl_add_u32 v148, s52, 8, v1
	v_ashrrev_i32_e32 v149, 31, v148
	v_lshl_add_u64 v[150:151], v[148:149], 2, s[26:27]
	global_load_dword v172, v[150:151], off
	global_load_dword v192, v[150:151], off offset:64
	global_load_dword v194, v[150:151], off offset:128
	global_load_dword v196, v[150:151], off offset:192
	global_load_dword v198, v[150:151], off offset:512
	global_load_dword v200, v[150:151], off offset:576
	global_load_dword v202, v[150:151], off offset:640
	global_load_dword v204, v[150:151], off offset:704
	v_cvt_f32_i32_e32 v175, v126
	v_cvt_f32_i32_e32 v174, v122
	v_cvt_f32_i32_e32 v177, v127
	v_cvt_f32_i32_e32 v176, v123
	v_cvt_f32_i32_e32 v179, v128
	v_cvt_f32_i32_e32 v178, v124
	v_cvt_f32_i32_e32 v180, v125
	v_cvt_f32_i32_e32 v187, v120
	v_cvt_f32_i32_e32 v189, v121
	v_cvt_f32_i32_e32 v181, v129
	v_cvt_f32_i32_e32 v183, v118
	v_cvt_f32_i32_e32 v182, v114
	v_cvt_f32_i32_e32 v185, v119
	v_cvt_f32_i32_e32 v184, v115
	v_cvt_f32_i32_e32 v186, v116
	v_cvt_f32_i32_e32 v188, v117
	v_cvt_f32_i32_e32 v111, v111
	v_cvt_f32_i32_e32 v103, v103
	v_cvt_f32_i32_e32 v113, v113
	v_cvt_f32_i32_e32 v105, v105
	v_cvt_f32_i32_e32 v95, v95
	v_cvt_f32_i32_e32 v87, v87
	v_cvt_f32_i32_e32 v97, v97
	v_cvt_f32_i32_e32 v89, v89
	v_cvt_f32_i32_e32 v79, v79
	v_cvt_f32_i32_e32 v71, v71
	v_cvt_f32_i32_e32 v81, v81
	v_cvt_f32_i32_e32 v73, v73
	v_cvt_f32_i32_e32 v63, v63
	v_cvt_f32_i32_e32 v55, v55
	v_cvt_f32_i32_e32 v65, v65
	v_cvt_f32_i32_e32 v57, v57
	v_cvt_f32_i32_e32 v47, v47
	v_cvt_f32_i32_e32 v49, v49
	v_cvt_f32_i32_e32 v39, v39
	v_cvt_f32_i32_e32 v41, v41
	v_cvt_f32_i32_e32 v31, v31
	v_cvt_f32_i32_e32 v33, v33
	v_cvt_f32_i32_e32 v23, v23
	v_cvt_f32_i32_e32 v25, v25
	v_cvt_f32_i32_e32 v15, v15
	v_cvt_f32_i32_e32 v17, v17
	v_cvt_f32_i32_e32 v7, v7
	v_cvt_f32_i32_e32 v9, v9
	s_andn2_b64 vcc, exec, s[6:7]
	s_waitcnt vmcnt(0)
	s_mov_b32 s98, 0x3c3a1e78
	s_mov_b32 s100, 0x3bb2d7c8
	v_pk_mul_f32 v[124:125], v[158:159], s[100:101] op_sel_hi:[1,0]
	v_pk_mul_f32 v[120:121], v[152:153], s[98:99] op_sel_hi:[1,0]
	v_pk_mul_f32 v[116:117], v[154:155], s[98:99] op_sel_hi:[1,0]
	v_pk_mul_f32 v[126:127], v[160:161], s[100:101] op_sel_hi:[1,0]
	v_pk_mul_f32 v[114:115], v[164:165], s[98:99] op_sel_hi:[1,0]
	v_pk_mul_f32 v[118:119], v[162:163], s[98:99] op_sel_hi:[1,0]
	v_pk_mul_f32 v[152:153], v[168:169], s[100:101] op_sel_hi:[1,0]
	v_pk_mul_f32 v[128:129], v[166:167], s[100:101] op_sel_hi:[1,0]
	v_mov_b32_e32 v122, v124
	v_mov_b32_e32 v123, v120
	v_mov_b32_e32 v120, v125
	v_mov_b32_e32 v124, v126
	v_mov_b32_e32 v125, v116
	v_mov_b32_e32 v116, v127
	v_mov_b32_e32 v126, v128
	v_mov_b32_e32 v127, v118
	v_mov_b32_e32 v118, v129
	v_mov_b32_e32 v128, v152
	v_mov_b32_e32 v129, v114
	v_mov_b32_e32 v114, v153
	v_pk_mul_f32 v[152:153], v[122:123], v[172:173] op_sel_hi:[1,0]
	v_pk_mul_f32 v[154:155], v[120:121], v[172:173] op_sel_hi:[1,0]
	v_pk_mul_f32 v[158:159], v[124:125], v[172:173] op_sel_hi:[1,0]
	v_pk_mul_f32 v[152:153], v[152:153], v[174:175]
	v_pk_mul_f32 v[154:155], v[154:155], v[176:177]
	v_pk_mul_f32 v[160:161], v[116:117], v[172:173] op_sel_hi:[1,0]
	v_pk_mul_f32 v[162:163], v[172:173], v[126:127] op_sel_hi:[0,1]
	v_pk_mul_f32 v[164:165], v[172:173], v[118:119] op_sel_hi:[0,1]
	v_pk_mul_f32 v[166:167], v[172:173], v[128:129] op_sel_hi:[0,1]
	v_pk_mul_f32 v[168:169], v[172:173], v[114:115] op_sel_hi:[0,1]
	v_pk_mul_f32 v[158:159], v[158:159], v[178:179]
	v_exp_f32_e64 v149, -v153
	v_exp_f32_e64 v172, -v155
	v_exp_f32_e64 v173, -v159
	v_pk_mul_f32 v[160:161], v[160:161], v[180:181]
	v_add_f32_e32 v149, 1.0, v149
	v_add_f32_e32 v172, 1.0, v172
	v_pk_mul_f32 v[162:163], v[162:163], v[182:183]
	v_add_f32_e32 v173, 1.0, v173
	v_rcp_f32_e32 v149, v149
	v_rcp_f32_e32 v172, v172
	v_rcp_f32_e32 v173, v173
	v_exp_f32_e64 v174, -v161
	v_exp_f32_e64 v175, -v163
	v_mul_f32_e32 v149, v153, v149
	v_mul_f32_e32 v153, v155, v172
	v_pk_mul_f32 v[164:165], v[164:165], v[184:185]
	v_mul_f32_e32 v155, v159, v173
	v_mul_f32_e32 v149, v152, v149
	v_mul_f32_e32 v154, v154, v153
	v_pk_mul_f32 v[152:153], v[168:169], v[188:189]
	v_pk_mul_f32 v[166:167], v[166:167], v[186:187]
	v_add_f32_e32 v174, 1.0, v174
	v_add_f32_e32 v175, 1.0, v175
	v_mul_f32_e32 v155, v158, v155
	v_exp_f32_e64 v176, -v165
	v_rcp_f32_e32 v174, v174
	v_rcp_f32_e32 v175, v175
	v_exp_f32_e64 v158, -v153
	v_exp_f32_e64 v177, -v167
	v_add_f32_e32 v176, 1.0, v176
	v_mul_f32_e32 v159, v161, v174
	v_mul_f32_e32 v161, v163, v175
	v_add_f32_e32 v158, 1.0, v158
	v_rcp_f32_e32 v176, v176
	v_mul_f32_e32 v159, v160, v159
	v_mul_f32_e32 v160, v162, v161
	v_add_f32_e32 v162, 1.0, v177
	v_rcp_f32_e32 v158, v158
	v_rcp_f32_e32 v162, v162
	v_mul_f32_e32 v161, v165, v176
	v_mul_f32_e32 v161, v164, v161
	v_mul_f32_e32 v153, v153, v158
	v_mul_f32_e32 v162, v167, v162
	v_mul_f32_e32 v152, v152, v153
	v_mul_f32_e32 v162, v166, v162
	v_cvt_pk_bf16_f32 v158, v149, v154
	v_cvt_pk_bf16_f32 v159, v155, v159
	v_cvt_pk_bf16_f32 v160, v160, v161
	v_cvt_pk_bf16_f32 v161, v162, v152
	v_mov_b64_e32 v[152:153], s[36:37]
	v_mad_i64_i32 v[162:163], s[0:1], v148, s76, v[152:153]
	v_lshlrev_b64 v[154:155], 1, v[170:171]
	v_lshl_add_u64 v[162:163], v[162:163], 0, v[154:155]
	global_store_dwordx4 v[162:163], v[158:161], off
	v_cvt_f32_i32_e32 v163, v110
	v_cvt_f32_i32_e32 v162, v106
	v_or_b32_e32 v158, 16, v148
	v_ashrrev_i32_e32 v159, 31, v158
	v_lshl_add_u64 v[160:161], v[158:159], 2, s[26:27]
	s_nop 1
	v_cvt_f32_i32_e32 v110, v107
	v_cvt_f32_i32_e32 v107, v112
	v_cvt_f32_i32_e32 v106, v108
	v_cvt_f32_i32_e32 v112, v109
	v_cvt_f32_i32_e32 v109, v102
	v_cvt_f32_i32_e32 v108, v98
	v_cvt_f32_i32_e32 v102, v99
	v_cvt_f32_i32_e32 v99, v104
	v_cvt_f32_i32_e32 v98, v100
	v_cvt_f32_i32_e32 v104, v101
	v_mov_b32_e32 v160, v192
	v_pk_mul_f32 v[170:171], v[126:127], v[160:161] op_sel_hi:[1,0]
	v_pk_mul_f32 v[100:101], v[122:123], v[160:161] op_sel_hi:[1,0]
	v_pk_mul_f32 v[108:109], v[170:171], v[108:109]
	v_pk_mul_f32 v[100:101], v[100:101], v[162:163]
	v_pk_mul_f32 v[164:165], v[120:121], v[160:161] op_sel_hi:[1,0]
	v_exp_f32_e64 v162, -v109
	v_pk_mul_f32 v[110:111], v[164:165], v[110:111]
	v_exp_f32_e64 v149, -v101
	v_exp_f32_e64 v159, -v111
	v_add_f32_e32 v162, 1.0, v162
	v_rcp_f32_e32 v162, v162
	v_pk_mul_f32 v[172:173], v[118:119], v[160:161] op_sel_hi:[1,0]
	v_pk_mul_f32 v[174:175], v[128:129], v[160:161] op_sel_hi:[1,0]
	v_pk_mul_f32 v[166:167], v[124:125], v[160:161] op_sel_hi:[1,0]
	v_pk_mul_f32 v[168:169], v[116:117], v[160:161] op_sel_hi:[1,0]
	v_pk_mul_f32 v[160:161], v[114:115], v[160:161] op_sel_hi:[1,0]
	v_pk_mul_f32 v[102:103], v[172:173], v[102:103]
	v_pk_mul_f32 v[98:99], v[174:175], v[98:99]
	v_add_f32_e32 v149, 1.0, v149
	v_add_f32_e32 v159, 1.0, v159
	v_pk_mul_f32 v[106:107], v[166:167], v[106:107]
	v_pk_mul_f32 v[112:113], v[168:169], v[112:113]
	v_pk_mul_f32 v[104:105], v[160:161], v[104:105]
	v_rcp_f32_e32 v149, v149
	v_rcp_f32_e32 v159, v159
	v_exp_f32_e64 v163, -v103
	v_exp_f32_e64 v164, -v99
	v_mul_f32_e32 v109, v109, v162
	v_exp_f32_e64 v160, -v107
	v_exp_f32_e64 v161, -v113
	v_mul_f32_e32 v108, v108, v109
	v_exp_f32_e64 v109, -v105
	v_mul_f32_e32 v101, v101, v149
	v_mul_f32_e32 v111, v111, v159
	v_add_f32_e32 v163, 1.0, v163
	v_mul_f32_e32 v100, v100, v101
	v_mul_f32_e32 v101, v110, v111
	v_add_f32_e32 v110, 1.0, v164
	v_add_f32_e32 v160, 1.0, v160
	v_add_f32_e32 v161, 1.0, v161
	v_rcp_f32_e32 v163, v163
	v_rcp_f32_e32 v110, v110
	v_add_f32_e32 v109, 1.0, v109
	v_rcp_f32_e32 v160, v160
	v_rcp_f32_e32 v161, v161
	v_rcp_f32_e32 v109, v109
	v_mul_f32_e32 v103, v103, v163
	v_mul_f32_e32 v99, v99, v110
	v_mul_f32_e32 v107, v107, v160
	v_mul_f32_e32 v113, v113, v161
	v_mul_f32_e32 v102, v102, v103
	v_mul_f32_e32 v103, v98, v99
	v_mul_f32_e32 v98, v105, v109
	v_mul_f32_e32 v106, v106, v107
	v_mul_f32_e32 v107, v112, v113
	v_mul_f32_e32 v104, v104, v98
	v_cvt_pk_bf16_f32 v98, v100, v101
	v_cvt_pk_bf16_f32 v99, v106, v107
	v_cvt_pk_bf16_f32 v100, v108, v102
	v_cvt_pk_bf16_f32 v101, v103, v104
	v_mad_i64_i32 v[102:103], s[0:1], v158, s76, v[152:153]
	v_lshl_add_u64 v[102:103], v[102:103], 0, v[154:155]
	global_store_dwordx4 v[102:103], v[98:101], off
	v_cvt_f32_i32_e32 v103, v94
	v_cvt_f32_i32_e32 v102, v90
	v_or_b32_e32 v98, 32, v148
	v_ashrrev_i32_e32 v99, 31, v98
	v_lshl_add_u64 v[100:101], v[98:99], 2, s[26:27]
	s_nop 1
	v_cvt_f32_i32_e32 v94, v91
	v_cvt_f32_i32_e32 v91, v96
	v_cvt_f32_i32_e32 v90, v92
	v_cvt_f32_i32_e32 v96, v93
	v_cvt_f32_i32_e32 v93, v86
	v_cvt_f32_i32_e32 v92, v82
	v_cvt_f32_i32_e32 v86, v83
	v_cvt_f32_i32_e32 v83, v88
	v_cvt_f32_i32_e32 v82, v84
	v_cvt_f32_i32_e32 v88, v85
	v_mov_b32_e32 v100, v194
	v_pk_mul_f32 v[110:111], v[126:127], v[100:101] op_sel_hi:[1,0]
	v_pk_mul_f32 v[84:85], v[122:123], v[100:101] op_sel_hi:[1,0]
	v_pk_mul_f32 v[92:93], v[110:111], v[92:93]
	v_pk_mul_f32 v[84:85], v[84:85], v[102:103]
	v_exp_f32_e64 v103, -v93
	v_pk_mul_f32 v[104:105], v[120:121], v[100:101] op_sel_hi:[1,0]
	v_pk_mul_f32 v[112:113], v[118:119], v[100:101] op_sel_hi:[1,0]
	v_pk_mul_f32 v[158:159], v[128:129], v[100:101] op_sel_hi:[1,0]
	v_pk_mul_f32 v[106:107], v[124:125], v[100:101] op_sel_hi:[1,0]
	v_pk_mul_f32 v[108:109], v[116:117], v[100:101] op_sel_hi:[1,0]
	v_pk_mul_f32 v[100:101], v[114:115], v[100:101] op_sel_hi:[1,0]
	v_pk_mul_f32 v[94:95], v[104:105], v[94:95]
	v_pk_mul_f32 v[86:87], v[112:113], v[86:87]
	v_pk_mul_f32 v[82:83], v[158:159], v[82:83]
	v_pk_mul_f32 v[90:91], v[106:107], v[90:91]
	v_pk_mul_f32 v[96:97], v[108:109], v[96:97]
	v_pk_mul_f32 v[88:89], v[100:101], v[88:89]
	v_add_f32_e32 v103, 1.0, v103
	v_exp_f32_e64 v99, -v85
	v_exp_f32_e64 v100, -v95
	v_exp_f32_e64 v104, -v87
	v_exp_f32_e64 v105, -v83
	v_rcp_f32_e32 v103, v103
	v_exp_f32_e64 v101, -v91
	v_exp_f32_e64 v102, -v97
	v_exp_f32_e64 v106, -v89
	v_add_f32_e32 v99, 1.0, v99
	v_add_f32_e32 v100, 1.0, v100
	v_add_f32_e32 v104, 1.0, v104
	v_add_f32_e32 v105, 1.0, v105
	v_mul_f32_e32 v93, v93, v103
	v_add_f32_e32 v101, 1.0, v101
	v_add_f32_e32 v102, 1.0, v102
	v_rcp_f32_e32 v99, v99
	v_rcp_f32_e32 v100, v100
	v_rcp_f32_e32 v104, v104
	v_rcp_f32_e32 v105, v105
	v_mul_f32_e32 v92, v92, v93
	v_add_f32_e32 v93, 1.0, v106
	v_rcp_f32_e32 v101, v101
	v_rcp_f32_e32 v102, v102
	v_rcp_f32_e32 v93, v93
	v_mul_f32_e32 v85, v85, v99
	v_mul_f32_e32 v95, v95, v100
	v_mul_f32_e32 v87, v87, v104
	v_mul_f32_e32 v83, v83, v105
	v_mul_f32_e32 v91, v91, v101
	v_mul_f32_e32 v97, v97, v102
	v_mul_f32_e32 v84, v84, v85
	v_mul_f32_e32 v85, v94, v95
	v_mul_f32_e32 v86, v86, v87
	v_mul_f32_e32 v87, v82, v83
	v_mul_f32_e32 v82, v89, v93
	v_mul_f32_e32 v90, v90, v91
	v_mul_f32_e32 v91, v96, v97
	v_mul_f32_e32 v88, v88, v82
	v_cvt_pk_bf16_f32 v82, v84, v85
	v_cvt_pk_bf16_f32 v83, v90, v91
	v_cvt_pk_bf16_f32 v84, v92, v86
	v_cvt_pk_bf16_f32 v85, v87, v88
	v_mad_i64_i32 v[86:87], s[0:1], v98, s76, v[152:153]
	v_lshl_add_u64 v[86:87], v[86:87], 0, v[154:155]
	global_store_dwordx4 v[86:87], v[82:85], off
	v_cvt_f32_i32_e32 v87, v78
	v_cvt_f32_i32_e32 v86, v74
	v_or_b32_e32 v82, 48, v148
	v_ashrrev_i32_e32 v83, 31, v82
	v_lshl_add_u64 v[84:85], v[82:83], 2, s[26:27]
	s_nop 1
	v_cvt_f32_i32_e32 v78, v75
	v_cvt_f32_i32_e32 v75, v80
	v_cvt_f32_i32_e32 v74, v76
	v_cvt_f32_i32_e32 v80, v77
	v_cvt_f32_i32_e32 v77, v70
	v_cvt_f32_i32_e32 v76, v66
	v_cvt_f32_i32_e32 v70, v67
	v_cvt_f32_i32_e32 v67, v72
	v_cvt_f32_i32_e32 v66, v68
	v_cvt_f32_i32_e32 v72, v69
	v_mov_b32_e32 v84, v196
	v_pk_mul_f32 v[68:69], v[122:123], v[84:85] op_sel_hi:[1,0]
	v_pk_mul_f32 v[88:89], v[120:121], v[84:85] op_sel_hi:[1,0]
	v_pk_mul_f32 v[96:97], v[118:119], v[84:85] op_sel_hi:[1,0]
	v_pk_mul_f32 v[98:99], v[128:129], v[84:85] op_sel_hi:[1,0]
	v_pk_mul_f32 v[90:91], v[124:125], v[84:85] op_sel_hi:[1,0]
	v_pk_mul_f32 v[92:93], v[116:117], v[84:85] op_sel_hi:[1,0]
	v_pk_mul_f32 v[94:95], v[126:127], v[84:85] op_sel_hi:[1,0]
	v_pk_mul_f32 v[84:85], v[114:115], v[84:85] op_sel_hi:[1,0]
	v_pk_mul_f32 v[68:69], v[68:69], v[86:87]
	v_pk_mul_f32 v[78:79], v[88:89], v[78:79]
	v_pk_mul_f32 v[70:71], v[96:97], v[70:71]
	v_pk_mul_f32 v[66:67], v[98:99], v[66:67]
	v_pk_mul_f32 v[74:75], v[90:91], v[74:75]
	v_pk_mul_f32 v[80:81], v[92:93], v[80:81]
	v_pk_mul_f32 v[76:77], v[94:95], v[76:77]
	v_pk_mul_f32 v[72:73], v[84:85], v[72:73]
	v_exp_f32_e64 v83, -v69
	v_exp_f32_e64 v84, -v79
	v_exp_f32_e64 v88, -v71
	v_exp_f32_e64 v89, -v67
	v_exp_f32_e64 v85, -v75
	v_exp_f32_e64 v86, -v81
	v_exp_f32_e64 v87, -v77
	v_exp_f32_e64 v90, -v73
	v_add_f32_e32 v83, 1.0, v83
	v_add_f32_e32 v84, 1.0, v84
	v_add_f32_e32 v88, 1.0, v88
	v_add_f32_e32 v89, 1.0, v89
	v_add_f32_e32 v85, 1.0, v85
	v_add_f32_e32 v86, 1.0, v86
	v_add_f32_e32 v87, 1.0, v87
	v_add_f32_e32 v90, 1.0, v90
	v_rcp_f32_e32 v83, v83
	v_rcp_f32_e32 v84, v84
	v_rcp_f32_e32 v88, v88
	v_rcp_f32_e32 v89, v89
	v_rcp_f32_e32 v85, v85
	v_rcp_f32_e32 v86, v86
	v_rcp_f32_e32 v87, v87
	v_rcp_f32_e32 v90, v90
	v_mul_f32_e32 v69, v69, v83
	v_mul_f32_e32 v79, v79, v84
	v_mul_f32_e32 v71, v71, v88
	v_mul_f32_e32 v67, v67, v89
	v_mul_f32_e32 v75, v75, v85
	v_mul_f32_e32 v81, v81, v86
	v_mul_f32_e32 v77, v77, v87
	v_mul_f32_e32 v68, v68, v69
	v_mul_f32_e32 v69, v78, v79
	v_mul_f32_e32 v70, v70, v71
	v_mul_f32_e32 v71, v66, v67
	v_mul_f32_e32 v66, v73, v90
	v_mul_f32_e32 v74, v74, v75
	v_mul_f32_e32 v75, v80, v81
	v_mul_f32_e32 v76, v76, v77
	v_mul_f32_e32 v72, v72, v66
	v_cvt_pk_bf16_f32 v66, v68, v69
	v_cvt_pk_bf16_f32 v67, v74, v75
	v_cvt_pk_bf16_f32 v68, v76, v70
	v_cvt_pk_bf16_f32 v69, v71, v72
	v_mad_i64_i32 v[70:71], s[0:1], v82, s76, v[152:153]
	v_lshl_add_u64 v[70:71], v[70:71], 0, v[154:155]
	global_store_dwordx4 v[70:71], v[66:69], off
	s_nop 1
	v_add_u32_e32 v82, 0x80, v148
	v_cvt_f32_i32_e32 v69, v62
	v_cvt_f32_i32_e32 v68, v58
	v_cvt_f32_i32_e32 v62, v59
	v_cvt_f32_i32_e32 v59, v64
	v_cvt_f32_i32_e32 v58, v60
	v_cvt_f32_i32_e32 v64, v61
	v_cvt_f32_i32_e32 v61, v54
	v_cvt_f32_i32_e32 v60, v50
	v_cvt_f32_i32_e32 v54, v51
	v_cvt_f32_i32_e32 v51, v56
	v_cvt_f32_i32_e32 v50, v52
	v_cvt_f32_i32_e32 v56, v53
	v_mov_b32_e32 v66, v198
	v_pk_mul_f32 v[52:53], v[122:123], v[66:67] op_sel_hi:[1,0]
	v_pk_mul_f32 v[70:71], v[120:121], v[66:67] op_sel_hi:[1,0]
	v_pk_mul_f32 v[78:79], v[118:119], v[66:67] op_sel_hi:[1,0]
	v_pk_mul_f32 v[80:81], v[128:129], v[66:67] op_sel_hi:[1,0]
	v_pk_mul_f32 v[72:73], v[124:125], v[66:67] op_sel_hi:[1,0]
	v_pk_mul_f32 v[74:75], v[116:117], v[66:67] op_sel_hi:[1,0]
	v_pk_mul_f32 v[76:77], v[126:127], v[66:67] op_sel_hi:[1,0]
	v_pk_mul_f32 v[66:67], v[114:115], v[66:67] op_sel_hi:[1,0]
	v_pk_mul_f32 v[52:53], v[52:53], v[68:69]
	v_pk_mul_f32 v[62:63], v[70:71], v[62:63]
	v_pk_mul_f32 v[54:55], v[78:79], v[54:55]
	v_pk_mul_f32 v[50:51], v[80:81], v[50:51]
	v_pk_mul_f32 v[58:59], v[72:73], v[58:59]
	v_pk_mul_f32 v[64:65], v[74:75], v[64:65]
	v_pk_mul_f32 v[60:61], v[76:77], v[60:61]
	v_pk_mul_f32 v[56:57], v[66:67], v[56:57]
	v_exp_f32_e64 v66, -v53
	v_exp_f32_e64 v67, -v63
	v_exp_f32_e64 v71, -v55
	v_exp_f32_e64 v72, -v51
	v_exp_f32_e64 v68, -v59
	v_exp_f32_e64 v69, -v65
	v_exp_f32_e64 v70, -v61
	v_exp_f32_e64 v73, -v57
	v_add_f32_e32 v66, 1.0, v66
	v_add_f32_e32 v67, 1.0, v67
	v_add_f32_e32 v71, 1.0, v71
	v_add_f32_e32 v72, 1.0, v72
	v_add_f32_e32 v68, 1.0, v68
	v_add_f32_e32 v69, 1.0, v69
	v_add_f32_e32 v70, 1.0, v70
	v_add_f32_e32 v73, 1.0, v73
	v_rcp_f32_e32 v66, v66
	v_rcp_f32_e32 v67, v67
	v_rcp_f32_e32 v71, v71
	v_rcp_f32_e32 v72, v72
	v_rcp_f32_e32 v68, v68
	v_rcp_f32_e32 v69, v69
	v_rcp_f32_e32 v70, v70
	v_rcp_f32_e32 v73, v73
	v_mul_f32_e32 v53, v53, v66
	v_mul_f32_e32 v63, v63, v67
	v_mul_f32_e32 v55, v55, v71
	v_mul_f32_e32 v51, v51, v72
	v_mul_f32_e32 v59, v59, v68
	v_mul_f32_e32 v65, v65, v69
	v_mul_f32_e32 v61, v61, v70
	v_mul_f32_e32 v57, v57, v73
	v_mul_f32_e32 v52, v52, v53
	v_mul_f32_e32 v53, v62, v63
	v_mul_f32_e32 v54, v54, v55
	v_mul_f32_e32 v55, v50, v51
	v_mul_f32_e32 v58, v58, v59
	v_mul_f32_e32 v59, v64, v65
	v_mul_f32_e32 v60, v60, v61
	v_mul_f32_e32 v56, v56, v57
	v_cvt_pk_bf16_f32 v50, v52, v53
	v_cvt_pk_bf16_f32 v51, v58, v59
	v_cvt_pk_bf16_f32 v52, v60, v54
	v_cvt_pk_bf16_f32 v53, v55, v56
	v_mad_i64_i32 v[54:55], s[0:1], v82, s76, v[152:153]
	v_lshl_add_u64 v[54:55], v[54:55], 0, v[154:155]
	global_store_dwordx4 v[54:55], v[50:53], off
	s_nop 1
	v_mov_b32_e32 v50, v200
	v_pk_mul_f32 v[56:57], v[120:121], v[50:51] op_sel_hi:[1,0]
	v_cvt_f32_i32_e32 v53, v46
	v_cvt_f32_i32_e32 v52, v42
	v_cvt_f32_i32_e32 v46, v43
	v_cvt_f32_i32_e32 v43, v48
	v_cvt_f32_i32_e32 v42, v44
	v_cvt_f32_i32_e32 v48, v45
	v_cvt_f32_i32_e32 v45, v38
	v_cvt_f32_i32_e32 v44, v34
	v_cvt_f32_i32_e32 v38, v35
	v_cvt_f32_i32_e32 v35, v40
	v_cvt_f32_i32_e32 v34, v36
	v_cvt_f32_i32_e32 v40, v37
	v_add_u32_e32 v36, 0x90, v148
	v_mad_i64_i32 v[36:37], s[0:1], v36, s76, v[152:153]
	v_lshl_add_u64 v[54:55], v[36:37], 0, v[154:155]
	v_pk_mul_f32 v[36:37], v[122:123], v[50:51] op_sel_hi:[1,0]
	v_pk_mul_f32 v[58:59], v[124:125], v[50:51] op_sel_hi:[1,0]
	v_pk_mul_f32 v[60:61], v[116:117], v[50:51] op_sel_hi:[1,0]
	v_pk_mul_f32 v[62:63], v[126:127], v[50:51] op_sel_hi:[1,0]
	v_pk_mul_f32 v[64:65], v[118:119], v[50:51] op_sel_hi:[1,0]
	v_pk_mul_f32 v[66:67], v[128:129], v[50:51] op_sel_hi:[1,0]
	v_pk_mul_f32 v[50:51], v[114:115], v[50:51] op_sel_hi:[1,0]
	v_pk_mul_f32 v[36:37], v[36:37], v[52:53]
	v_pk_mul_f32 v[46:47], v[56:57], v[46:47]
	v_pk_mul_f32 v[42:43], v[58:59], v[42:43]
	v_pk_mul_f32 v[48:49], v[60:61], v[48:49]
	v_pk_mul_f32 v[44:45], v[62:63], v[44:45]
	v_pk_mul_f32 v[38:39], v[64:65], v[38:39]
	v_pk_mul_f32 v[34:35], v[66:67], v[34:35]
	v_pk_mul_f32 v[40:41], v[50:51], v[40:41]
	v_exp_f32_e64 v50, -v37
	v_exp_f32_e64 v51, -v47
	v_exp_f32_e64 v52, -v43
	v_exp_f32_e64 v53, -v49
	v_exp_f32_e64 v56, -v45
	v_exp_f32_e64 v57, -v39
	v_exp_f32_e64 v58, -v35
	v_exp_f32_e64 v59, -v41
	v_add_f32_e32 v50, 1.0, v50
	v_add_f32_e32 v51, 1.0, v51
	v_add_f32_e32 v52, 1.0, v52
	v_add_f32_e32 v53, 1.0, v53
	v_add_f32_e32 v56, 1.0, v56
	v_add_f32_e32 v57, 1.0, v57
	v_add_f32_e32 v58, 1.0, v58
	v_add_f32_e32 v59, 1.0, v59
	v_rcp_f32_e32 v50, v50
	v_rcp_f32_e32 v51, v51
	v_rcp_f32_e32 v52, v52
	v_rcp_f32_e32 v53, v53
	v_rcp_f32_e32 v56, v56
	v_rcp_f32_e32 v57, v57
	v_rcp_f32_e32 v58, v58
	v_rcp_f32_e32 v59, v59
	v_mul_f32_e32 v37, v37, v50
	v_mul_f32_e32 v47, v47, v51
	v_mul_f32_e32 v43, v43, v52
	v_mul_f32_e32 v49, v49, v53
	v_mul_f32_e32 v45, v45, v56
	v_mul_f32_e32 v39, v39, v57
	v_mul_f32_e32 v35, v35, v58
	v_mul_f32_e32 v41, v41, v59
	v_mul_f32_e32 v36, v36, v37
	v_mul_f32_e32 v37, v46, v47
	v_mul_f32_e32 v42, v42, v43
	v_mul_f32_e32 v43, v48, v49
	v_mul_f32_e32 v44, v44, v45
	v_mul_f32_e32 v38, v38, v39
	v_mul_f32_e32 v39, v34, v35
	v_mul_f32_e32 v40, v40, v41
	v_cvt_pk_bf16_f32 v34, v36, v37
	v_cvt_pk_bf16_f32 v35, v42, v43
	v_cvt_pk_bf16_f32 v36, v44, v38
	v_cvt_pk_bf16_f32 v37, v39, v40
	global_store_dwordx4 v[54:55], v[34:37], off
	s_nop 1
	v_mov_b32_e32 v34, v202
	v_pk_mul_f32 v[40:41], v[120:121], v[34:35] op_sel_hi:[1,0]
	v_cvt_f32_i32_e32 v37, v30
	v_cvt_f32_i32_e32 v36, v26
	v_cvt_f32_i32_e32 v30, v27
	v_cvt_f32_i32_e32 v27, v32
	v_cvt_f32_i32_e32 v26, v28
	v_cvt_f32_i32_e32 v32, v29
	v_cvt_f32_i32_e32 v29, v22
	v_cvt_f32_i32_e32 v28, v18
	v_cvt_f32_i32_e32 v22, v19
	v_cvt_f32_i32_e32 v19, v24
	v_cvt_f32_i32_e32 v18, v20
	v_cvt_f32_i32_e32 v24, v21
	v_add_u32_e32 v20, 0xa0, v148
	v_mad_i64_i32 v[20:21], s[0:1], v20, s76, v[152:153]
	v_lshl_add_u64 v[38:39], v[20:21], 0, v[154:155]
	v_pk_mul_f32 v[20:21], v[122:123], v[34:35] op_sel_hi:[1,0]
	v_pk_mul_f32 v[42:43], v[124:125], v[34:35] op_sel_hi:[1,0]
	v_pk_mul_f32 v[44:45], v[116:117], v[34:35] op_sel_hi:[1,0]
	v_pk_mul_f32 v[46:47], v[126:127], v[34:35] op_sel_hi:[1,0]
	v_pk_mul_f32 v[48:49], v[118:119], v[34:35] op_sel_hi:[1,0]
	v_pk_mul_f32 v[50:51], v[128:129], v[34:35] op_sel_hi:[1,0]
	v_pk_mul_f32 v[34:35], v[114:115], v[34:35] op_sel_hi:[1,0]
	v_pk_mul_f32 v[20:21], v[20:21], v[36:37]
	v_pk_mul_f32 v[30:31], v[40:41], v[30:31]
	v_pk_mul_f32 v[26:27], v[42:43], v[26:27]
	v_pk_mul_f32 v[32:33], v[44:45], v[32:33]
	v_pk_mul_f32 v[28:29], v[46:47], v[28:29]
	v_pk_mul_f32 v[22:23], v[48:49], v[22:23]
	v_pk_mul_f32 v[18:19], v[50:51], v[18:19]
	v_pk_mul_f32 v[24:25], v[34:35], v[24:25]
	v_exp_f32_e64 v34, -v21
	v_exp_f32_e64 v35, -v31
	v_exp_f32_e64 v36, -v27
	v_exp_f32_e64 v37, -v33
	v_exp_f32_e64 v40, -v29
	v_exp_f32_e64 v41, -v23
	v_exp_f32_e64 v42, -v19
	v_exp_f32_e64 v43, -v25
	v_add_f32_e32 v34, 1.0, v34
	v_add_f32_e32 v35, 1.0, v35
	v_add_f32_e32 v36, 1.0, v36
	v_add_f32_e32 v37, 1.0, v37
	v_add_f32_e32 v40, 1.0, v40
	v_add_f32_e32 v41, 1.0, v41
	v_add_f32_e32 v42, 1.0, v42
	v_add_f32_e32 v43, 1.0, v43
	v_rcp_f32_e32 v34, v34
	v_rcp_f32_e32 v35, v35
	v_rcp_f32_e32 v36, v36
	v_rcp_f32_e32 v37, v37
	v_rcp_f32_e32 v40, v40
	v_rcp_f32_e32 v41, v41
	v_rcp_f32_e32 v42, v42
	v_rcp_f32_e32 v43, v43
	v_mul_f32_e32 v21, v21, v34
	v_mul_f32_e32 v31, v31, v35
	v_mul_f32_e32 v27, v27, v36
	v_mul_f32_e32 v33, v33, v37
	v_mul_f32_e32 v29, v29, v40
	v_mul_f32_e32 v23, v23, v41
	v_mul_f32_e32 v19, v19, v42
	v_mul_f32_e32 v25, v25, v43
	v_mul_f32_e32 v20, v20, v21
	v_mul_f32_e32 v21, v30, v31
	v_mul_f32_e32 v26, v26, v27
	v_mul_f32_e32 v27, v32, v33
	v_mul_f32_e32 v28, v28, v29
	v_mul_f32_e32 v22, v22, v23
	v_mul_f32_e32 v23, v18, v19
	v_mul_f32_e32 v24, v24, v25
	v_cvt_pk_bf16_f32 v18, v20, v21
	v_cvt_pk_bf16_f32 v19, v26, v27
	v_cvt_pk_bf16_f32 v20, v28, v22
	v_cvt_pk_bf16_f32 v21, v23, v24
	global_store_dwordx4 v[38:39], v[18:21], off
	s_nop 1
	v_mov_b32_e32 v18, v204
	v_pk_mul_f32 v[24:25], v[120:121], v[18:19] op_sel_hi:[1,0]
	v_cvt_f32_i32_e32 v21, v14
	v_cvt_f32_i32_e32 v20, v10
	v_cvt_f32_i32_e32 v14, v11
	v_cvt_f32_i32_e32 v11, v16
	v_cvt_f32_i32_e32 v10, v12
	v_cvt_f32_i32_e32 v16, v13
	v_cvt_f32_i32_e32 v13, v6
	v_cvt_f32_i32_e32 v12, v2
	v_cvt_f32_i32_e32 v6, v3
	v_cvt_f32_i32_e32 v3, v8
	v_cvt_f32_i32_e32 v2, v4
	v_cvt_f32_i32_e32 v8, v5
	v_add_u32_e32 v4, 0xb0, v148
	v_mad_i64_i32 v[4:5], s[0:1], v4, s76, v[152:153]
	v_lshl_add_u64 v[22:23], v[4:5], 0, v[154:155]
	v_pk_mul_f32 v[4:5], v[122:123], v[18:19] op_sel_hi:[1,0]
	v_pk_mul_f32 v[26:27], v[124:125], v[18:19] op_sel_hi:[1,0]
	v_pk_mul_f32 v[28:29], v[116:117], v[18:19] op_sel_hi:[1,0]
	v_pk_mul_f32 v[30:31], v[126:127], v[18:19] op_sel_hi:[1,0]
	v_pk_mul_f32 v[32:33], v[118:119], v[18:19] op_sel_hi:[1,0]
	v_pk_mul_f32 v[34:35], v[128:129], v[18:19] op_sel_hi:[1,0]
	v_pk_mul_f32 v[18:19], v[114:115], v[18:19] op_sel_hi:[1,0]
	v_pk_mul_f32 v[4:5], v[4:5], v[20:21]
	v_pk_mul_f32 v[14:15], v[24:25], v[14:15]
	v_pk_mul_f32 v[10:11], v[26:27], v[10:11]
	v_pk_mul_f32 v[16:17], v[28:29], v[16:17]
	v_pk_mul_f32 v[12:13], v[30:31], v[12:13]
	v_pk_mul_f32 v[6:7], v[32:33], v[6:7]
	v_pk_mul_f32 v[2:3], v[34:35], v[2:3]
	v_pk_mul_f32 v[8:9], v[18:19], v[8:9]
	v_exp_f32_e64 v18, -v5
	v_exp_f32_e64 v19, -v15
	v_exp_f32_e64 v20, -v11
	v_exp_f32_e64 v21, -v17
	v_exp_f32_e64 v24, -v13
	v_exp_f32_e64 v25, -v7
	v_exp_f32_e64 v26, -v3
	v_exp_f32_e64 v27, -v9
	v_add_f32_e32 v18, 1.0, v18
	v_add_f32_e32 v19, 1.0, v19
	v_add_f32_e32 v20, 1.0, v20
	v_add_f32_e32 v21, 1.0, v21
	v_add_f32_e32 v24, 1.0, v24
	v_add_f32_e32 v25, 1.0, v25
	v_add_f32_e32 v26, 1.0, v26
	v_add_f32_e32 v27, 1.0, v27
	v_rcp_f32_e32 v18, v18
	v_rcp_f32_e32 v19, v19
	v_rcp_f32_e32 v20, v20
	v_rcp_f32_e32 v21, v21
	v_rcp_f32_e32 v24, v24
	v_rcp_f32_e32 v25, v25
	v_rcp_f32_e32 v26, v26
	v_rcp_f32_e32 v27, v27
	v_mul_f32_e32 v5, v5, v18
	v_mul_f32_e32 v15, v15, v19
	v_mul_f32_e32 v11, v11, v20
	v_mul_f32_e32 v17, v17, v21
	v_mul_f32_e32 v13, v13, v24
	v_mul_f32_e32 v7, v7, v25
	v_mul_f32_e32 v3, v3, v26
	v_mul_f32_e32 v9, v9, v27
	v_mul_f32_e32 v4, v4, v5
	v_mul_f32_e32 v5, v14, v15
	s_mov_b64 s[0:1], -1
	v_mul_f32_e32 v10, v10, v11
	v_mul_f32_e32 v11, v16, v17
	v_mul_f32_e32 v12, v12, v13
	v_mul_f32_e32 v6, v6, v7
	v_mul_f32_e32 v7, v2, v3
	v_mul_f32_e32 v8, v8, v9
	v_cvt_pk_bf16_f32 v2, v4, v5
	v_cvt_pk_bf16_f32 v3, v10, v11
	v_cvt_pk_bf16_f32 v4, v12, v6
	v_cvt_pk_bf16_f32 v5, v7, v8
	global_store_dwordx4 v[22:23], v[2:5], off
	s_cbranch_vccnz .LBB0_1412
	s_andn2_b64 vcc, exec, s[18:19]
	s_cbranch_vccnz .LBB0_1411
	s_barrier
	s_branch .LBB0_1411

	.amdhsa_kernel _Z6mk_fwd4Args
		.amdhsa_group_segment_fixed_size 0
		.amdhsa_private_segment_fixed_size 0
		.amdhsa_kernarg_size 432
		.amdhsa_user_sgpr_count 2
		.amdhsa_user_sgpr_dispatch_ptr 0
		.amdhsa_user_sgpr_queue_ptr 0
		.amdhsa_user_sgpr_kernarg_segment_ptr 1
		.amdhsa_user_sgpr_dispatch_id 0
		.amdhsa_user_sgpr_kernarg_preload_length 0
		.amdhsa_user_sgpr_kernarg_preload_offset 0
		.amdhsa_user_sgpr_private_segment_size 0
		.amdhsa_uses_dynamic_stack 0
		.amdhsa_enable_private_segment 0
		.amdhsa_system_sgpr_workgroup_id_x 1
		.amdhsa_system_sgpr_workgroup_id_y 0
		.amdhsa_system_sgpr_workgroup_id_z 0
		.amdhsa_system_sgpr_workgroup_info 0
		.amdhsa_system_vgpr_workitem_id 0
		.amdhsa_next_free_vgpr 224
		.amdhsa_next_free_sgpr 102
		.amdhsa_accum_offset 224
		.amdhsa_reserve_vcc 1
		.amdhsa_float_round_mode_32 0
		.amdhsa_float_round_mode_16_64 0
		.amdhsa_float_denorm_mode_32 3
		.amdhsa_float_denorm_mode_16_64 3
		.amdhsa_dx10_clamp 1
		.amdhsa_ieee_mode 1
		.amdhsa_fp16_overflow 0
		.amdhsa_tg_split 0
		.amdhsa_exception_fp_ieee_invalid_op 0
		.amdhsa_exception_fp_denorm_src 0
		.amdhsa_exception_fp_ieee_div_zero 0
		.amdhsa_exception_fp_ieee_overflow 0
		.amdhsa_exception_fp_ieee_underflow 0
		.amdhsa_exception_fp_ieee_inexact 0
		.amdhsa_exception_int_div_zero 0
	.end_amdhsa_kernel

amdhsa.kernels:
  - .agpr_count:     0
    .args:
      - .offset:         0
        .size:           176
        .value_kind:     by_value
      - .offset:         176
        .size:           4
        .value_kind:     hidden_block_count_x
      - .offset:         180
        .size:           4
        .value_kind:     hidden_block_count_y
      - .offset:         184
        .size:           4
        .value_kind:     hidden_block_count_z
      - .offset:         188
        .size:           2
        .value_kind:     hidden_group_size_x
      - .offset:         190
        .size:           2
        .value_kind:     hidden_group_size_y
      - .offset:         192
        .size:           2
        .value_kind:     hidden_group_size_z
      - .offset:         194
        .size:           2
        .value_kind:     hidden_remainder_x
      - .offset:         196
        .size:           2
        .value_kind:     hidden_remainder_y
      - .offset:         198
        .size:           2
        .value_kind:     hidden_remainder_z
      - .offset:         216
        .size:           8
        .value_kind:     hidden_global_offset_x
      - .offset:         224
        .size:           8
        .value_kind:     hidden_global_offset_y
      - .offset:         232
        .size:           8
        .value_kind:     hidden_global_offset_z
      - .offset:         240
        .size:           2
        .value_kind:     hidden_grid_dims
      - .offset:         296
        .size:           4
        .value_kind:     hidden_dynamic_lds_size
    .group_segment_fixed_size: 0
    .kernarg_segment_align: 8
    .kernarg_segment_size: 432
    .language:       OpenCL C
    .language_version:
      - 2
      - 0
    .max_flat_workgroup_size: 512
    .name:           _Z6mk_fwd4Args
    .private_segment_fixed_size: 0
    .sgpr_count:     108
    .sgpr_spill_count: 145
    .symbol:         _Z6mk_fwd4Args.kd
    .uniform_work_group_size: 1
    .uses_dynamic_stack: false
    .vgpr_count:     224
    .vgpr_spill_count: 0
    .wavefront_size: 64
